# P0 transposes pipelined + sample MLA QK ring + KN stat loads batched + FFN-up stats prefetch
# speedup vs baseline: 1.0250x; 1.0220x over previous
; __global__ void __launch_bounds__(512, 2) fwd_mega(Params P) {
;     ...
; #pragma unroll 16
;                 for (int i = 0; i < 32; ++i) { const int kk = 2 * i + (lane >> 5); float v = c >= 0 ? W[(size_t)(k0 + kk) * ldw + c] : 0.f; if (gk) v *= gk[k0 + kk]; scr[kk * 33 + (lane & 31)] = v; }
;                 asm volatile("s_waitcnt lgkmcnt(0)" ::: "memory");
.LBB0_60:
	s_add_i32 s54, s54, 32
	v_add_u32_e32 v7, 0x1080, v7
	s_cmp_eq_u32 s54, 64
	v_lshl_add_u64 v[10:11], v[10:11], 0, s[26:27]
	s_cbranch_scc1 .LBB0_7
.LBB0_61:
	v_mov_b32_e32 v80, 0
	v_mov_b32_e32 v81, 0
	v_mov_b32_e32 v82, 0
	v_mov_b32_e32 v83, 0
	v_mov_b32_e32 v84, 0
	v_mov_b32_e32 v85, 0
	v_mov_b32_e32 v86, 0
	v_mov_b32_e32 v87, 0
	v_mov_b32_e32 v88, 0
	v_mov_b32_e32 v89, 0
	v_mov_b32_e32 v90, 0
	v_mov_b32_e32 v91, 0
	v_mov_b32_e32 v92, 0
	v_mov_b32_e32 v93, 0
	v_mov_b32_e32 v94, 0
	v_mov_b32_e32 v95, 0
	v_cndmask_b32_e64 v21, 0, 1, s[36:37]
	v_cmp_ne_u32_e64 s[10:11], 1, v21
	s_and_saveexec_b64 s[38:39], s[8:9]
	s_cbranch_execz .Lmy_tr_noload
	v_add_u32_e32 v12, s54, v4
	v_ashrrev_i32_e32 v13, 31, v12
	v_mul_lo_u32 v20, s34, v13
	v_mul_lo_u32 v21, s35, v12
	v_mad_u64_u32 v[12:13], s[56:57], s34, v12, 0
	v_add3_u32 v13, v13, v20, v21
	v_lshl_add_u64 v[12:13], v[12:13], 2, v[8:9]
	global_load_dword v80, v[12:13], off
	v_add3_u32 v12, v4, s54, 2
	v_ashrrev_i32_e32 v13, 31, v12
	v_mul_lo_u32 v20, s34, v13
	v_mul_lo_u32 v21, s35, v12
	v_mad_u64_u32 v[12:13], s[56:57], s34, v12, 0
	v_add3_u32 v13, v13, v20, v21
	v_lshl_add_u64 v[12:13], v[12:13], 2, v[8:9]
	global_load_dword v81, v[12:13], off
	v_add3_u32 v12, v4, s54, 4
	v_ashrrev_i32_e32 v13, 31, v12
	v_mul_lo_u32 v20, s34, v13
	v_mul_lo_u32 v21, s35, v12
	v_mad_u64_u32 v[12:13], s[56:57], s34, v12, 0
	v_add3_u32 v13, v13, v20, v21
	v_lshl_add_u64 v[12:13], v[12:13], 2, v[8:9]
	global_load_dword v82, v[12:13], off
	v_add3_u32 v12, v4, s54, 6
	v_ashrrev_i32_e32 v13, 31, v12
	v_mul_lo_u32 v20, s34, v13
	v_mul_lo_u32 v21, s35, v12
	v_mad_u64_u32 v[12:13], s[56:57], s34, v12, 0
	v_add3_u32 v13, v13, v20, v21
	v_lshl_add_u64 v[12:13], v[12:13], 2, v[8:9]
	global_load_dword v83, v[12:13], off
	v_add3_u32 v12, v4, s54, 8
	v_ashrrev_i32_e32 v13, 31, v12
	v_mul_lo_u32 v20, s34, v13
	v_mul_lo_u32 v21, s35, v12
	v_mad_u64_u32 v[12:13], s[56:57], s34, v12, 0
	v_add3_u32 v13, v13, v20, v21
	v_lshl_add_u64 v[12:13], v[12:13], 2, v[8:9]
	global_load_dword v84, v[12:13], off
	v_add3_u32 v12, v4, s54, 10
	v_ashrrev_i32_e32 v13, 31, v12
	v_mul_lo_u32 v20, s34, v13
	v_mul_lo_u32 v21, s35, v12
	v_mad_u64_u32 v[12:13], s[56:57], s34, v12, 0
	v_add3_u32 v13, v13, v20, v21
	v_lshl_add_u64 v[12:13], v[12:13], 2, v[8:9]
	global_load_dword v85, v[12:13], off
	v_add3_u32 v12, v4, s54, 12
	v_ashrrev_i32_e32 v13, 31, v12
	v_mul_lo_u32 v20, s34, v13
	v_mul_lo_u32 v21, s35, v12
	v_mad_u64_u32 v[12:13], s[56:57], s34, v12, 0
	v_add3_u32 v13, v13, v20, v21
	v_lshl_add_u64 v[12:13], v[12:13], 2, v[8:9]
	global_load_dword v86, v[12:13], off
	v_add3_u32 v12, v4, s54, 14
	v_ashrrev_i32_e32 v13, 31, v12
	v_mul_lo_u32 v20, s34, v13
	v_mul_lo_u32 v21, s35, v12
	v_mad_u64_u32 v[12:13], s[56:57], s34, v12, 0
	v_add3_u32 v13, v13, v20, v21
	v_lshl_add_u64 v[12:13], v[12:13], 2, v[8:9]
	global_load_dword v87, v[12:13], off
	v_add3_u32 v12, v4, s54, 16
	v_ashrrev_i32_e32 v13, 31, v12
	v_mul_lo_u32 v20, s34, v13
	v_mul_lo_u32 v21, s35, v12
	v_mad_u64_u32 v[12:13], s[56:57], s34, v12, 0
	v_add3_u32 v13, v13, v20, v21
	v_lshl_add_u64 v[12:13], v[12:13], 2, v[8:9]
	global_load_dword v88, v[12:13], off
	v_add3_u32 v12, v4, s54, 18
	v_ashrrev_i32_e32 v13, 31, v12
	v_mul_lo_u32 v20, s34, v13
	v_mul_lo_u32 v21, s35, v12
	v_mad_u64_u32 v[12:13], s[56:57], s34, v12, 0
	v_add3_u32 v13, v13, v20, v21
	v_lshl_add_u64 v[12:13], v[12:13], 2, v[8:9]
	global_load_dword v89, v[12:13], off
	v_add3_u32 v12, v4, s54, 20
	v_ashrrev_i32_e32 v13, 31, v12
	v_mul_lo_u32 v20, s34, v13
	v_mul_lo_u32 v21, s35, v12
	v_mad_u64_u32 v[12:13], s[56:57], s34, v12, 0
	v_add3_u32 v13, v13, v20, v21
	v_lshl_add_u64 v[12:13], v[12:13], 2, v[8:9]
	global_load_dword v90, v[12:13], off
	v_add3_u32 v12, v4, s54, 22
	v_ashrrev_i32_e32 v13, 31, v12
	v_mul_lo_u32 v20, s34, v13
	v_mul_lo_u32 v21, s35, v12
	v_mad_u64_u32 v[12:13], s[56:57], s34, v12, 0
	v_add3_u32 v13, v13, v20, v21
	v_lshl_add_u64 v[12:13], v[12:13], 2, v[8:9]
	global_load_dword v91, v[12:13], off
	v_add3_u32 v12, v4, s54, 24
	v_ashrrev_i32_e32 v13, 31, v12
	v_mul_lo_u32 v20, s34, v13
	v_mul_lo_u32 v21, s35, v12
	v_mad_u64_u32 v[12:13], s[56:57], s34, v12, 0
	v_add3_u32 v13, v13, v20, v21
	v_lshl_add_u64 v[12:13], v[12:13], 2, v[8:9]
	global_load_dword v92, v[12:13], off
	v_add3_u32 v12, v4, s54, 26
	v_ashrrev_i32_e32 v13, 31, v12
	v_mul_lo_u32 v20, s34, v13
	v_mul_lo_u32 v21, s35, v12
	v_mad_u64_u32 v[12:13], s[56:57], s34, v12, 0
	v_add3_u32 v13, v13, v20, v21
	v_lshl_add_u64 v[12:13], v[12:13], 2, v[8:9]
	global_load_dword v93, v[12:13], off
	v_add3_u32 v12, v4, s54, 28
	v_ashrrev_i32_e32 v13, 31, v12
	v_mul_lo_u32 v20, s34, v13
	v_mul_lo_u32 v21, s35, v12
	v_mad_u64_u32 v[12:13], s[56:57], s34, v12, 0
	v_add3_u32 v13, v13, v20, v21
	v_lshl_add_u64 v[12:13], v[12:13], 2, v[8:9]
	global_load_dword v94, v[12:13], off
	v_add3_u32 v12, v4, s54, 30
	v_ashrrev_i32_e32 v13, 31, v12
	v_mul_lo_u32 v20, s34, v13
	v_mul_lo_u32 v21, s35, v12
	v_mad_u64_u32 v[12:13], s[56:57], s34, v12, 0
	v_add3_u32 v13, v13, v20, v21
	v_lshl_add_u64 v[12:13], v[12:13], 2, v[8:9]
	global_load_dword v95, v[12:13], off
; __global__ void __launch_bounds__(512, 2) fwd_mega(Params P) {
;     ...
; #pragma unroll 16
;                 for (int i = 0; i < 32; ++i) { const int kk = 2 * i + (lane >> 5); float v = c >= 0 ? W[(size_t)(k0 + kk) * ldw + c] : 0.f; if (gk) v *= gk[k0 + kk]; scr[kk * 33 + (lane & 31)] = v; }
;                 asm volatile("s_waitcnt lgkmcnt(0)" ::: "memory");
.Lmy_tr_noload:
	s_or_b64 exec, exec, s[38:39]
	s_andn2_b64 vcc, exec, s[36:37]
	s_cbranch_vccnz .Lmy_tr_nogk
	global_load_dword v96, v[10:11], off offset:-120
	global_load_dword v97, v[10:11], off offset:-112
	global_load_dword v98, v[10:11], off offset:-104
	global_load_dword v99, v[10:11], off offset:-96
	global_load_dword v100, v[10:11], off offset:-88
	global_load_dword v101, v[10:11], off offset:-80
	global_load_dword v102, v[10:11], off offset:-72
	global_load_dword v103, v[10:11], off offset:-64
	global_load_dword v104, v[10:11], off offset:-56
	global_load_dword v105, v[10:11], off offset:-48
	global_load_dword v106, v[10:11], off offset:-40
	global_load_dword v107, v[10:11], off offset:-32
	global_load_dword v108, v[10:11], off offset:-24
	global_load_dword v109, v[10:11], off offset:-16
	global_load_dword v110, v[10:11], off offset:-8
	global_load_dword v111, v[10:11], off
	s_waitcnt vmcnt(15)
	v_mul_f32_e32 v80, v80, v96
	ds_write_b32 v7, v80
	s_waitcnt vmcnt(14)
	v_mul_f32_e32 v81, v81, v97
	ds_write_b32 v7, v81 offset:264
	s_waitcnt vmcnt(13)
	v_mul_f32_e32 v82, v82, v98
	ds_write_b32 v7, v82 offset:528
	s_waitcnt vmcnt(12)
	v_mul_f32_e32 v83, v83, v99
	ds_write_b32 v7, v83 offset:792
	s_waitcnt vmcnt(11)
	v_mul_f32_e32 v84, v84, v100
	ds_write_b32 v7, v84 offset:1056
	s_waitcnt vmcnt(10)
	v_mul_f32_e32 v85, v85, v101
	ds_write_b32 v7, v85 offset:1320
	s_waitcnt vmcnt(9)
	v_mul_f32_e32 v86, v86, v102
	ds_write_b32 v7, v86 offset:1584
	s_waitcnt vmcnt(8)
	v_mul_f32_e32 v87, v87, v103
	ds_write_b32 v7, v87 offset:1848
	s_waitcnt vmcnt(7)
	v_mul_f32_e32 v88, v88, v104
	ds_write_b32 v7, v88 offset:2112
	s_waitcnt vmcnt(6)
	v_mul_f32_e32 v89, v89, v105
	ds_write_b32 v7, v89 offset:2376
	s_waitcnt vmcnt(5)
	v_mul_f32_e32 v90, v90, v106
	ds_write_b32 v7, v90 offset:2640
	s_waitcnt vmcnt(4)
	v_mul_f32_e32 v91, v91, v107
	ds_write_b32 v7, v91 offset:2904
	s_waitcnt vmcnt(3)
	v_mul_f32_e32 v92, v92, v108
	ds_write_b32 v7, v92 offset:3168
	s_waitcnt vmcnt(2)
	v_mul_f32_e32 v93, v93, v109
	ds_write_b32 v7, v93 offset:3432
	s_waitcnt vmcnt(1)
	v_mul_f32_e32 v94, v94, v110
	ds_write_b32 v7, v94 offset:3696
	s_waitcnt vmcnt(0)
	v_mul_f32_e32 v95, v95, v111
	ds_write_b32 v7, v95 offset:3960
	s_branch .LBB0_60
.Lmy_tr_nogk:
	s_waitcnt vmcnt(15)
	ds_write_b32 v7, v80
	s_waitcnt vmcnt(14)
	ds_write_b32 v7, v81 offset:264
	s_waitcnt vmcnt(13)
	ds_write_b32 v7, v82 offset:528
	s_waitcnt vmcnt(12)
	ds_write_b32 v7, v83 offset:792
	s_waitcnt vmcnt(11)
	ds_write_b32 v7, v84 offset:1056
	s_waitcnt vmcnt(10)
	ds_write_b32 v7, v85 offset:1320
	s_waitcnt vmcnt(9)
	ds_write_b32 v7, v86 offset:1584
	s_waitcnt vmcnt(8)
	ds_write_b32 v7, v87 offset:1848
	s_waitcnt vmcnt(7)
	ds_write_b32 v7, v88 offset:2112
	s_waitcnt vmcnt(6)
	ds_write_b32 v7, v89 offset:2376
	s_waitcnt vmcnt(5)
	ds_write_b32 v7, v90 offset:2640
	s_waitcnt vmcnt(4)
	ds_write_b32 v7, v91 offset:2904
	s_waitcnt vmcnt(3)
	ds_write_b32 v7, v92 offset:3168
	s_waitcnt vmcnt(2)
	ds_write_b32 v7, v93 offset:3432
	s_waitcnt vmcnt(1)
	ds_write_b32 v7, v94 offset:3696
	s_waitcnt vmcnt(0)
	ds_write_b32 v7, v95 offset:3960
	s_branch .LBB0_60

; #define PG8_STAGE(bufoff, gbase, voff) do { _Pragma("unroll") for (int _i = 0; _i < 2; ++_i) \
;         __builtin_amdgcn_global_load_lds((const unsigned*)((const char*)(gbase) + (size_t)_i * vst##voff + v##voff), (LAS unsigned*)(lds + (bufoff) + ldsw + _i * 8192), 16, 0, 0); } while (0)
; #define PG8_LDA(dst, b, h) do { _Pragma("unroll") for (int m = 0; m < 4; ++m) _Pragma("unroll") for (int k = 0; k < 2; ++k) dst[m][k] = *(const LAS bf16x8*)(lds + PG8_SA(b, h) + aoff + m * 2048 + k * 1024); } while (0)
; #define PG8_LDB(dst, b, h) do { _Pragma("unroll") for (int n = 0; n < 2; ++n) _Pragma("unroll") for (int k = 0; k < 2; ++k) dst[n][k] = *(const LAS bf16x8*)(lds + PG8_SB(b, h) + boff + n * 2048 + k * 1024); } while (0)
; #define PG8_MMA(ai, bj, At, Bt) do { __builtin_amdgcn_s_setprio(1); _Pragma("unroll") for (int m = 0; m < 4; ++m) _Pragma("unroll") for (int n = 0; n < 2; ++n) _Pragma("unroll") for (int k = 0; k < 2; ++k) \
;         acc[ai][bj][m][n] = __builtin_amdgcn_mfma_f32_16x16x32_bf16(Bt[n][k], At[m][k], acc[ai][bj][m][n], 0, 0, 0); __builtin_amdgcn_s_setprio(0); } while (0)
; #define PG8_WAIT_L(n) asm volatile("s_waitcnt lgkmcnt(" #n ")" ::: "memory")
; #define PG8_BAR __builtin_amdgcn_s_barrier()
; #define PG8_SCHED __builtin_amdgcn_sched_barrier(0)
; template <class Epi>
; DI void gemm_phase(LAS unsigned char* lds, const Gemm g, const StaticOrder& S, const Epi& E, const int tid) {
;     ...
;             PG8_LDB(B0, 0, 0); PG8_SCHED; PG8_LDA(At, 0, 0); PG8_STAGE(PG8_SA(1, 1), a1 + hsA, offA);
;             PG8_WAIT_L(8); PG8_BAR; PG8_WAIT_L(0); PG8_MMA(0, 0, At, B0); PG8_BAR; PG8_SCHED;
;             PG8_LDB(B1, 0, 1); PG8_STAGE(PG8_SB(0, 0), b2, offB);
;             PG8_BAR; PG8_WAIT_L(0); PG8_MMA(0, 1, At, B1); PG8_BAR;
;             PG8_LDA(At, 0, 1); PG8_STAGE(PG8_SA(0, 0), a2, offA);
;             PG8_BAR; PG8_WAIT_L(0); PG8_MMA(1, 0, At, B0); PG8_BAR; PG8_SCHED;
.LBB0_1118:
	s_ashr_i32 s23, s22, 31
	s_lshl_b64 s[6:7], s[22:23], 17
	s_add_u32 s26, s37, s6
	s_addc_u32 s27, s38, s7
	s_and_b64 s[6:7], s[12:13], exec
	s_cselect_b32 s13, s27, s29
	s_cselect_b32 s12, s26, s28
	s_add_i32 s87, 0, 0x10000
	v_add_u32_e32 v188, s87, v138
	ds_read_b128 v[4:7], v188
	ds_read_b128 v[8:11], v188 offset:1024
	ds_read_b128 v[12:15], v188 offset:2048
	ds_read_b128 v[16:19], v188 offset:3072
	v_lshl_add_u64 v[2:3], s[30:31], 0, v[130:131]
	s_mov_b64 s[4:5], 0x1b0080
	s_add_i32 s31, s40, 0xc000
	v_lshl_add_u64 v[52:53], v[2:3], 0, s[4:5]
	s_mov_b32 m0, s31
	s_mov_b64 s[4:5], 0x288080
	s_add_i32 s23, s40, 0xe000
	ds_read_b128 v[20:23], v139
	ds_read_b128 v[24:27], v139 offset:1024
	ds_read_b128 v[28:31], v139 offset:2048
	ds_read_b128 v[32:35], v139 offset:3072
	ds_read_b128 v[36:39], v139 offset:4096
	ds_read_b128 v[40:43], v139 offset:5120
	ds_read_b128 v[44:47], v139 offset:6144
	ds_read_b128 v[48:51], v139 offset:7168
	global_load_lds_dwordx4 v[52:53], off
	v_lshl_add_u64 v[52:53], v[2:3], 0, s[4:5]
	s_mov_b32 m0, s23
	s_nop 0
	global_load_lds_dwordx4 v[52:53], off
	s_waitcnt lgkmcnt(8)
	s_barrier
	s_waitcnt lgkmcnt(0)
	s_setprio 1
	s_waitcnt lgkmcnt(0)
	v_mfma_f32_16x16x32_bf16 v[52:55], v[4:7], v[20:23], 0
	v_mfma_f32_16x16x32_bf16 v[56:59], v[12:15], v[20:23], 0
	v_mfma_f32_16x16x32_bf16 v[60:63], v[4:7], v[28:31], 0
	v_mfma_f32_16x16x32_bf16 v[64:67], v[12:15], v[28:31], 0
	v_mfma_f32_16x16x32_bf16 v[68:71], v[4:7], v[36:39], 0
	v_mfma_f32_16x16x32_bf16 v[72:75], v[12:15], v[36:39], 0
	v_mfma_f32_16x16x32_bf16 v[76:79], v[4:7], v[44:47], 0
	v_mfma_f32_16x16x32_bf16 v[80:83], v[12:15], v[44:47], 0
	v_mfma_f32_16x16x32_bf16 v[52:55], v[8:11], v[24:27], v[52:55]
	v_mfma_f32_16x16x32_bf16 v[56:59], v[16:19], v[24:27], v[56:59]
	v_mfma_f32_16x16x32_bf16 v[60:63], v[8:11], v[32:35], v[60:63]
	v_mfma_f32_16x16x32_bf16 v[64:67], v[16:19], v[32:35], v[64:67]
	v_mfma_f32_16x16x32_bf16 v[68:71], v[8:11], v[40:43], v[68:71]
	v_mfma_f32_16x16x32_bf16 v[72:75], v[16:19], v[40:43], v[72:75]
	v_mfma_f32_16x16x32_bf16 v[76:79], v[8:11], v[48:51], v[76:79]
	v_mfma_f32_16x16x32_bf16 v[80:83], v[16:19], v[48:51], v[80:83]
	s_setprio 0
	s_barrier
	s_add_i32 s30, 0, 0x14000
	v_lshl_add_u64 v[128:129], s[28:29], 0, v[0:1]
	s_mov_b64 s[6:7], 0x100
	s_add_i32 s87, s87, s39
	v_add_u32_e32 v189, s30, v138
	v_lshl_add_u64 v[100:101], v[128:129], 0, s[6:7]
	s_mov_b32 m0, s87
	s_mov_b64 s[4:5], 0x8100
	s_add_i32 s28, s87, 0x2000
	ds_read_b128 v[84:87], v189
	ds_read_b128 v[88:91], v189 offset:1024
	ds_read_b128 v[92:95], v189 offset:2048
	ds_read_b128 v[96:99], v189 offset:3072
	global_load_lds_dwordx4 v[100:101], off
	v_lshl_add_u64 v[100:101], v[128:129], 0, s[4:5]
	s_mov_b32 m0, s28
	s_nop 0
	global_load_lds_dwordx4 v[100:101], off
	s_barrier
	s_waitcnt lgkmcnt(0)
	s_setprio 1
	s_waitcnt lgkmcnt(0)
	v_mfma_f32_16x16x32_bf16 v[100:103], v[84:87], v[20:23], 0
	v_mfma_f32_16x16x32_bf16 v[20:23], v[92:95], v[20:23], 0
	v_mfma_f32_16x16x32_bf16 v[100:103], v[88:91], v[24:27], v[100:103]
	v_mfma_f32_16x16x32_bf16 v[20:23], v[96:99], v[24:27], v[20:23]
	v_mfma_f32_16x16x32_bf16 v[24:27], v[84:87], v[28:31], 0
	v_mfma_f32_16x16x32_bf16 v[28:31], v[92:95], v[28:31], 0
	v_mfma_f32_16x16x32_bf16 v[24:27], v[88:91], v[32:35], v[24:27]
	v_mfma_f32_16x16x32_bf16 v[28:31], v[96:99], v[32:35], v[28:31]
	v_mfma_f32_16x16x32_bf16 v[32:35], v[84:87], v[36:39], 0
	v_mfma_f32_16x16x32_bf16 v[36:39], v[92:95], v[36:39], 0
	v_mfma_f32_16x16x32_bf16 v[32:35], v[88:91], v[40:43], v[32:35]
	v_mfma_f32_16x16x32_bf16 v[36:39], v[96:99], v[40:43], v[36:39]
	v_mfma_f32_16x16x32_bf16 v[40:43], v[84:87], v[44:47], 0
	v_mfma_f32_16x16x32_bf16 v[44:47], v[92:95], v[44:47], 0
	v_mfma_f32_16x16x32_bf16 v[40:43], v[88:91], v[48:51], v[40:43]
	v_mfma_f32_16x16x32_bf16 v[44:47], v[96:99], v[48:51], v[44:47]
	s_setprio 0
	s_mov_b32 m0, s40
	v_lshl_add_u64 v[136:137], v[2:3], 0, s[6:7]
	s_mov_b64 s[4:5], 0xd8100
	s_barrier
	ds_read_b128 v[48:51], v139 offset:16384
	ds_read_b128 v[104:107], v139 offset:17408
	ds_read_b128 v[108:111], v139 offset:18432
	ds_read_b128 v[112:115], v139 offset:19456
	ds_read_b128 v[116:119], v139 offset:20480
	ds_read_b128 v[120:123], v139 offset:21504
	ds_read_b128 v[124:127], v139 offset:22528
	ds_read_b128 v[132:135], v139 offset:23552
	global_load_lds_dwordx4 v[136:137], off
	v_lshl_add_u64 v[136:137], v[2:3], 0, s[4:5]
	s_mov_b32 m0, s41
	s_nop 0
	global_load_lds_dwordx4 v[136:137], off
	s_barrier
	s_waitcnt lgkmcnt(0)
	s_setprio 1
	s_waitcnt lgkmcnt(0)
	v_mfma_f32_16x16x32_bf16 v[140:143], v[4:7], v[48:51], 0
	v_mfma_f32_16x16x32_bf16 v[148:151], v[4:7], v[108:111], 0
	v_mfma_f32_16x16x32_bf16 v[156:159], v[4:7], v[116:119], 0
	v_mfma_f32_16x16x32_bf16 v[4:7], v[4:7], v[124:127], 0
	v_mfma_f32_16x16x32_bf16 v[140:143], v[8:11], v[104:107], v[140:143]
	v_mfma_f32_16x16x32_bf16 v[144:147], v[12:15], v[48:51], 0
	v_mfma_f32_16x16x32_bf16 v[148:151], v[8:11], v[112:115], v[148:151]
	v_mfma_f32_16x16x32_bf16 v[156:159], v[8:11], v[120:123], v[156:159]
	v_mfma_f32_16x16x32_bf16 v[4:7], v[8:11], v[132:135], v[4:7]
	v_mfma_f32_16x16x32_bf16 v[8:11], v[12:15], v[124:127], 0
	v_mfma_f32_16x16x32_bf16 v[144:147], v[16:19], v[104:107], v[144:147]
	v_mfma_f32_16x16x32_bf16 v[152:155], v[12:15], v[108:111], 0
	v_mfma_f32_16x16x32_bf16 v[160:163], v[12:15], v[116:119], 0
	v_mfma_f32_16x16x32_bf16 v[8:11], v[16:19], v[132:135], v[8:11]
	v_mfma_f32_16x16x32_bf16 v[152:155], v[16:19], v[112:115], v[152:155]
	v_mfma_f32_16x16x32_bf16 v[160:163], v[16:19], v[120:123], v[160:163]
	s_setprio 0
	s_barrier
; #define PG8_STAGE(bufoff, gbase, voff) do { _Pragma("unroll") for (int _i = 0; _i < 2; ++_i) \
;         __builtin_amdgcn_global_load_lds((const unsigned*)((const char*)(gbase) + (size_t)_i * vst##voff + v##voff), (LAS unsigned*)(lds + (bufoff) + ldsw + _i * 8192), 16, 0, 0); } while (0)
; #define PG8_LDA(dst, b, h) do { _Pragma("unroll") for (int m = 0; m < 4; ++m) _Pragma("unroll") for (int k = 0; k < 2; ++k) dst[m][k] = *(const LAS bf16x8*)(lds + PG8_SA(b, h) + aoff + m * 2048 + k * 1024); } while (0)
; #define PG8_LDB(dst, b, h) do { _Pragma("unroll") for (int n = 0; n < 2; ++n) _Pragma("unroll") for (int k = 0; k < 2; ++k) dst[n][k] = *(const LAS bf16x8*)(lds + PG8_SB(b, h) + boff + n * 2048 + k * 1024); } while (0)
; #define PG8_MMA(ai, bj, At, Bt) do { __builtin_amdgcn_s_setprio(1); _Pragma("unroll") for (int m = 0; m < 4; ++m) _Pragma("unroll") for (int n = 0; n < 2; ++n) _Pragma("unroll") for (int k = 0; k < 2; ++k) \
;         acc[ai][bj][m][n] = __builtin_amdgcn_mfma_f32_16x16x32_bf16(Bt[n][k], At[m][k], acc[ai][bj][m][n], 0, 0, 0); __builtin_amdgcn_s_setprio(0); } while (0)
; #define PG8_WAIT_V(n) asm volatile("s_waitcnt vmcnt(" #n ")" ::: "memory")
; #define PG8_WAIT_L(n) asm volatile("s_waitcnt lgkmcnt(" #n ")" ::: "memory")
; #define PG8_BAR __builtin_amdgcn_s_barrier()
; #define PG8_SCHED __builtin_amdgcn_sched_barrier(0)
; template <class Epi>
; DI void gemm_phase(LAS unsigned char* lds, const Gemm g, const StaticOrder& S, const Epi& E, const int tid) {
;     ...
;             PG8_STAGE(PG8_SB(0, 1), b2 + hsB, offB);
;             PG8_WAIT_V(6); PG8_BAR; PG8_MMA(1, 1, At, B1); PG8_BAR;
;             PG8_LDB(B0, 1, 0); PG8_SCHED; PG8_LDA(At, 1, 0); PG8_STAGE(PG8_SA(0, 1), a2 + hsA, offA);
;             PG8_WAIT_L(8); PG8_BAR; PG8_WAIT_L(0); PG8_MMA(0, 0, At, B0); PG8_BAR; PG8_SCHED;
;             PG8_LDB(B1, 1, 1); PG8_STAGE(PG8_SB(1, 0), b3, offB);
;             PG8_BAR; PG8_WAIT_L(0); PG8_MMA(0, 1, At, B1); PG8_BAR;
;             PG8_LDA(At, 1, 1); PG8_STAGE(PG8_SA(1, 0), a3, offA);
	s_mov_b64 s[4:5], 0x10100
	s_add_i32 s30, s30, s39
	v_lshl_add_u64 v[12:13], v[128:129], 0, s[4:5]
	s_mov_b32 m0, s30
	s_mov_b64 s[4:5], 0x18100
	s_add_i32 s29, s30, 0x2000
	global_load_lds_dwordx4 v[12:13], off
	v_lshl_add_u64 v[12:13], v[128:129], 0, s[4:5]
	s_mov_b32 m0, s29
	s_nop 0
	global_load_lds_dwordx4 v[12:13], off
	s_waitcnt vmcnt(6)
	s_barrier
	s_setprio 1
	v_mfma_f32_16x16x32_bf16 v[12:15], v[84:87], v[48:51], 0
	v_mfma_f32_16x16x32_bf16 v[16:19], v[92:95], v[48:51], 0
	v_mfma_f32_16x16x32_bf16 v[12:15], v[88:91], v[104:107], v[12:15]
	v_mfma_f32_16x16x32_bf16 v[16:19], v[96:99], v[104:107], v[16:19]
	v_mfma_f32_16x16x32_bf16 v[48:51], v[84:87], v[108:111], 0
	v_mfma_f32_16x16x32_bf16 v[104:107], v[92:95], v[108:111], 0
	v_mfma_f32_16x16x32_bf16 v[108:111], v[84:87], v[116:119], 0
	v_mfma_f32_16x16x32_bf16 v[84:87], v[84:87], v[124:127], 0
	v_mfma_f32_16x16x32_bf16 v[48:51], v[88:91], v[112:115], v[48:51]
	v_mfma_f32_16x16x32_bf16 v[104:107], v[96:99], v[112:115], v[104:107]
	v_mfma_f32_16x16x32_bf16 v[108:111], v[88:91], v[120:123], v[108:111]
	v_mfma_f32_16x16x32_bf16 v[112:115], v[92:95], v[116:119], 0
	v_mfma_f32_16x16x32_bf16 v[84:87], v[88:91], v[132:135], v[84:87]
	v_mfma_f32_16x16x32_bf16 v[88:91], v[92:95], v[124:127], 0
	v_mfma_f32_16x16x32_bf16 v[112:115], v[96:99], v[120:123], v[112:115]
	v_mfma_f32_16x16x32_bf16 v[88:91], v[96:99], v[132:135], v[88:91]
	s_setprio 0
	s_add_i32 vcc_lo, 0, 0x18000
	v_add_u32_e32 v190, vcc_lo, v138
	s_barrier
	ds_read_b128 v[92:95], v190
	ds_read_b128 v[96:99], v190 offset:1024
	ds_read_b128 v[116:119], v190 offset:2048
	ds_read_b128 v[120:123], v190 offset:3072
	s_mov_b64 s[4:5], 0x1b0100
	s_mov_b32 m0, s42
	v_lshl_add_u64 v[136:137], v[2:3], 0, s[4:5]
	s_mov_b64 s[4:5], 0x288100
	ds_read_b128 v[124:127], v139 offset:32768
	ds_read_b128 v[132:135], v139 offset:33792
	ds_read_b128 v[164:167], v139 offset:34816
	ds_read_b128 v[168:171], v139 offset:35840
	ds_read_b128 v[172:175], v139 offset:36864
	ds_read_b128 v[176:179], v139 offset:37888
	ds_read_b128 v[180:183], v139 offset:38912
	ds_read_b128 v[184:187], v139 offset:39936
	global_load_lds_dwordx4 v[136:137], off
	v_lshl_add_u64 v[136:137], v[2:3], 0, s[4:5]
	s_mov_b32 m0, s43
	s_nop 0
	global_load_lds_dwordx4 v[136:137], off
	s_waitcnt lgkmcnt(8)
	s_barrier
	s_waitcnt lgkmcnt(0)
	s_setprio 1
	s_waitcnt lgkmcnt(0)
	v_mfma_f32_16x16x32_bf16 v[52:55], v[92:95], v[124:127], v[52:55]
	v_mfma_f32_16x16x32_bf16 v[56:59], v[116:119], v[124:127], v[56:59]
	v_mfma_f32_16x16x32_bf16 v[60:63], v[92:95], v[164:167], v[60:63]
	v_mfma_f32_16x16x32_bf16 v[64:67], v[116:119], v[164:167], v[64:67]
	v_mfma_f32_16x16x32_bf16 v[68:71], v[92:95], v[172:175], v[68:71]
	v_mfma_f32_16x16x32_bf16 v[72:75], v[116:119], v[172:175], v[72:75]
	v_mfma_f32_16x16x32_bf16 v[76:79], v[92:95], v[180:183], v[76:79]
	v_mfma_f32_16x16x32_bf16 v[80:83], v[116:119], v[180:183], v[80:83]
	v_mfma_f32_16x16x32_bf16 v[52:55], v[96:99], v[132:135], v[52:55]
	v_mfma_f32_16x16x32_bf16 v[56:59], v[120:123], v[132:135], v[56:59]
	v_mfma_f32_16x16x32_bf16 v[60:63], v[96:99], v[168:171], v[60:63]
	v_mfma_f32_16x16x32_bf16 v[64:67], v[120:123], v[168:171], v[64:67]
	v_mfma_f32_16x16x32_bf16 v[68:71], v[96:99], v[176:179], v[68:71]
	v_mfma_f32_16x16x32_bf16 v[72:75], v[120:123], v[176:179], v[72:75]
	v_mfma_f32_16x16x32_bf16 v[76:79], v[96:99], v[184:187], v[76:79]
	v_mfma_f32_16x16x32_bf16 v[80:83], v[120:123], v[184:187], v[80:83]
	s_setprio 0
	s_barrier
	s_add_i32 vcc_hi, 0, 0x1c000
	s_mov_b64 s[34:35], 0x180
	s_add_i32 vcc_lo, vcc_lo, s39
	v_add_u32_e32 v191, vcc_hi, v138
	v_lshl_add_u64 v[136:137], v[128:129], 0, s[34:35]
	s_mov_b32 m0, vcc_lo
	s_mov_b64 s[4:5], 0x8180
	s_add_i32 s6, vcc_lo, 0x2000
	ds_read_b128 v[192:195], v191
	ds_read_b128 v[196:199], v191 offset:1024
	ds_read_b128 v[200:203], v191 offset:2048
	ds_read_b128 v[204:207], v191 offset:3072
	global_load_lds_dwordx4 v[136:137], off
	v_lshl_add_u64 v[136:137], v[128:129], 0, s[4:5]
	s_mov_b32 m0, s6
	s_nop 0
	global_load_lds_dwordx4 v[136:137], off
	s_barrier
	s_waitcnt lgkmcnt(0)
	s_setprio 1
	s_waitcnt lgkmcnt(0)
	v_mfma_f32_16x16x32_bf16 v[100:103], v[192:195], v[124:127], v[100:103]
	v_mfma_f32_16x16x32_bf16 v[20:23], v[200:203], v[124:127], v[20:23]
	v_mfma_f32_16x16x32_bf16 v[24:27], v[192:195], v[164:167], v[24:27]
	v_mfma_f32_16x16x32_bf16 v[28:31], v[200:203], v[164:167], v[28:31]
	v_mfma_f32_16x16x32_bf16 v[32:35], v[192:195], v[172:175], v[32:35]
	v_mfma_f32_16x16x32_bf16 v[36:39], v[200:203], v[172:175], v[36:39]
	v_mfma_f32_16x16x32_bf16 v[40:43], v[192:195], v[180:183], v[40:43]
	v_mfma_f32_16x16x32_bf16 v[44:47], v[200:203], v[180:183], v[44:47]
	v_mfma_f32_16x16x32_bf16 v[100:103], v[196:199], v[132:135], v[100:103]
	v_mfma_f32_16x16x32_bf16 v[20:23], v[204:207], v[132:135], v[20:23]
	v_mfma_f32_16x16x32_bf16 v[24:27], v[196:199], v[168:171], v[24:27]
	v_mfma_f32_16x16x32_bf16 v[28:31], v[204:207], v[168:171], v[28:31]
	v_mfma_f32_16x16x32_bf16 v[32:35], v[196:199], v[176:179], v[32:35]
	v_mfma_f32_16x16x32_bf16 v[36:39], v[204:207], v[176:179], v[36:39]
	v_mfma_f32_16x16x32_bf16 v[40:43], v[196:199], v[184:187], v[40:43]
	v_mfma_f32_16x16x32_bf16 v[44:47], v[204:207], v[184:187], v[44:47]
	s_setprio 0
	s_mov_b32 m0, s47
	v_lshl_add_u64 v[136:137], v[2:3], 0, s[34:35]
	s_mov_b64 s[4:5], 0xd8180
	s_barrier
	ds_read_b128 v[124:127], v139 offset:49152
	ds_read_b128 v[132:135], v139 offset:50176
	ds_read_b128 v[164:167], v139 offset:51200
	ds_read_b128 v[168:171], v139 offset:52224
	ds_read_b128 v[172:175], v139 offset:53248
	ds_read_b128 v[176:179], v139 offset:54272
	ds_read_b128 v[180:183], v139 offset:55296
	ds_read_b128 v[184:187], v139 offset:56320
	global_load_lds_dwordx4 v[136:137], off
	v_lshl_add_u64 v[136:137], v[2:3], 0, s[4:5]
	s_mov_b32 m0, s58
	s_nop 0
	global_load_lds_dwordx4 v[136:137], off
	s_barrier
; #define PG8_STAGE(bufoff, gbase, voff) do { _Pragma("unroll") for (int _i = 0; _i < 2; ++_i) \
;         __builtin_amdgcn_global_load_lds((const unsigned*)((const char*)(gbase) + (size_t)_i * vst##voff + v##voff), (LAS unsigned*)(lds + (bufoff) + ldsw + _i * 8192), 16, 0, 0); } while (0)
; #define PG8_LDA(dst, b, h) do { _Pragma("unroll") for (int m = 0; m < 4; ++m) _Pragma("unroll") for (int k = 0; k < 2; ++k) dst[m][k] = *(const LAS bf16x8*)(lds + PG8_SA(b, h) + aoff + m * 2048 + k * 1024); } while (0)
; #define PG8_LDB(dst, b, h) do { _Pragma("unroll") for (int n = 0; n < 2; ++n) _Pragma("unroll") for (int k = 0; k < 2; ++k) dst[n][k] = *(const LAS bf16x8*)(lds + PG8_SB(b, h) + boff + n * 2048 + k * 1024); } while (0)
; #define PG8_WAIT_V(n) asm volatile("s_waitcnt vmcnt(" #n ")" ::: "memory")
; #define PG8_WAIT_L(n) asm volatile("s_waitcnt lgkmcnt(" #n ")" ::: "memory")
; #define PG8_BAR __builtin_amdgcn_s_barrier()
; #define PG8_SCHED __builtin_amdgcn_sched_barrier(0)
; template <class Epi>
; DI void gemm_phase(LAS unsigned char* lds, const Gemm g, const StaticOrder& S, const Epi& E, const int tid) {
;     ...
;             PG8_LDB(B0, 0, 0); PG8_SCHED; PG8_LDA(At, 0, 0); PG8_STAGE(PG8_SA(1, 1), a1 + hsA, offA);
;             PG8_WAIT_L(8); PG8_BAR; PG8_WAIT_L(0); PG8_MMA(0, 0, At, B0); PG8_BAR; PG8_SCHED;
;             PG8_LDB(B1, 0, 1); PG8_STAGE(PG8_SB(0, 0), b2, offB);
;             PG8_BAR; PG8_WAIT_L(0); PG8_MMA(0, 1, At, B1); PG8_BAR;
;             PG8_LDA(At, 0, 1); PG8_STAGE(PG8_SA(0, 0), a2, offA);
;             PG8_BAR; PG8_WAIT_L(0); PG8_MMA(1, 0, At, B0); PG8_BAR; PG8_SCHED;
;             PG8_STAGE(PG8_SB(0, 1), b2 + hsB, offB);
;             PG8_WAIT_V(6); PG8_BAR; PG8_MMA(1, 1, At, B1); PG8_BAR;
;             PG8_LDB(B0, 1, 0); PG8_SCHED; PG8_LDA(At, 1, 0); PG8_STAGE(PG8_SA(0, 1), a2 + hsA, offA);
;             PG8_WAIT_L(8); PG8_BAR; PG8_WAIT_L(0); PG8_MMA(0, 0, At, B0); PG8_BAR; PG8_SCHED;
;             PG8_LDB(B1, 1, 1); PG8_STAGE(PG8_SB(1, 0), b3, offB);
;             PG8_BAR; PG8_WAIT_L(0); PG8_MMA(0, 1, At, B1); PG8_BAR;
;             PG8_LDA(At, 1, 1); PG8_STAGE(PG8_SA(1, 0), a3, offA);
;             PG8_BAR; PG8_WAIT_L(0); PG8_MMA(1, 0, At, B0); PG8_BAR; PG8_SCHED;
;             PG8_STAGE(PG8_SB(1, 1), b3 + hsB, offB);
;             PG8_WAIT_V(6); PG8_BAR; PG8_MMA(1, 1, At, B1); PG8_BAR;
	s_waitcnt lgkmcnt(0)
	s_setprio 1
	s_waitcnt lgkmcnt(0)
	v_mfma_f32_16x16x32_bf16 v[144:147], v[116:119], v[124:127], v[144:147]
	v_mfma_f32_16x16x32_bf16 v[4:7], v[92:95], v[180:183], v[4:7]
	v_mfma_f32_16x16x32_bf16 v[8:11], v[116:119], v[180:183], v[8:11]
	v_mfma_f32_16x16x32_bf16 v[140:143], v[92:95], v[124:127], v[140:143]
	v_mfma_f32_16x16x32_bf16 v[144:147], v[120:123], v[132:135], v[144:147]
	v_mfma_f32_16x16x32_bf16 v[148:151], v[92:95], v[164:167], v[148:151]
	v_mfma_f32_16x16x32_bf16 v[152:155], v[116:119], v[164:167], v[152:155]
	v_mfma_f32_16x16x32_bf16 v[156:159], v[92:95], v[172:175], v[156:159]
	v_mfma_f32_16x16x32_bf16 v[160:163], v[116:119], v[172:175], v[160:163]
	v_mfma_f32_16x16x32_bf16 v[4:7], v[96:99], v[184:187], v[4:7]
	v_mfma_f32_16x16x32_bf16 v[8:11], v[120:123], v[184:187], v[8:11]
	v_mfma_f32_16x16x32_bf16 v[140:143], v[96:99], v[132:135], v[140:143]
	v_mfma_f32_16x16x32_bf16 v[148:151], v[96:99], v[168:171], v[148:151]
	v_mfma_f32_16x16x32_bf16 v[152:155], v[120:123], v[168:171], v[152:155]
	v_mfma_f32_16x16x32_bf16 v[156:159], v[96:99], v[176:179], v[156:159]
	v_mfma_f32_16x16x32_bf16 v[160:163], v[120:123], v[176:179], v[160:163]
	s_setprio 0
	s_barrier
	s_mov_b64 s[4:5], 0x10180
	s_add_i32 vcc_hi, vcc_hi, s39
	v_lshl_add_u64 v[92:93], v[128:129], 0, s[4:5]
	s_mov_b32 m0, vcc_hi
	s_mov_b64 s[4:5], 0x18180
	s_add_i32 s36, vcc_hi, 0x2000
	global_load_lds_dwordx4 v[92:93], off
	v_lshl_add_u64 v[92:93], v[128:129], 0, s[4:5]
	s_mov_b32 m0, s36
	s_nop 0
	global_load_lds_dwordx4 v[92:93], off
	s_waitcnt vmcnt(6)
	s_barrier
	s_setprio 1
	v_mfma_f32_16x16x32_bf16 v[12:15], v[192:195], v[124:127], v[12:15]
	v_mfma_f32_16x16x32_bf16 v[16:19], v[200:203], v[124:127], v[16:19]
	v_mfma_f32_16x16x32_bf16 v[48:51], v[192:195], v[164:167], v[48:51]
	v_mfma_f32_16x16x32_bf16 v[92:95], v[200:203], v[164:167], v[104:107]
	v_mfma_f32_16x16x32_bf16 v[96:99], v[192:195], v[172:175], v[108:111]
	v_mfma_f32_16x16x32_bf16 v[104:107], v[200:203], v[172:175], v[112:115]
	v_mfma_f32_16x16x32_bf16 v[84:87], v[192:195], v[180:183], v[84:87]
	v_mfma_f32_16x16x32_bf16 v[88:91], v[200:203], v[180:183], v[88:91]
	v_mfma_f32_16x16x32_bf16 v[12:15], v[196:199], v[132:135], v[12:15]
	v_mfma_f32_16x16x32_bf16 v[16:19], v[204:207], v[132:135], v[16:19]
	v_mfma_f32_16x16x32_bf16 v[48:51], v[196:199], v[168:171], v[48:51]
	v_mfma_f32_16x16x32_bf16 v[92:95], v[204:207], v[168:171], v[92:95]
	v_mfma_f32_16x16x32_bf16 v[96:99], v[196:199], v[176:179], v[96:99]
	v_mfma_f32_16x16x32_bf16 v[104:107], v[204:207], v[176:179], v[104:107]
	v_mfma_f32_16x16x32_bf16 v[84:87], v[196:199], v[184:187], v[84:87]
	v_mfma_f32_16x16x32_bf16 v[88:91], v[204:207], v[184:187], v[88:91]
	s_setprio 0
	s_barrier
	ds_read_b128 v[108:111], v188
	ds_read_b128 v[112:115], v188 offset:1024
	ds_read_b128 v[116:119], v188 offset:2048
	ds_read_b128 v[120:123], v188 offset:3072
	s_mov_b64 s[4:5], 0x1b0180
	s_mov_b32 m0, s31
	v_lshl_add_u64 v[128:129], v[2:3], 0, s[4:5]
	s_mov_b64 s[4:5], 0x288180
	ds_read_b128 v[124:127], v139
	ds_read_b128 v[132:135], v139 offset:1024
	ds_read_b128 v[164:167], v139 offset:2048
	ds_read_b128 v[168:171], v139 offset:3072
	ds_read_b128 v[172:175], v139 offset:4096
	ds_read_b128 v[176:179], v139 offset:5120
	ds_read_b128 v[180:183], v139 offset:6144
	ds_read_b128 v[184:187], v139 offset:7168
	global_load_lds_dwordx4 v[128:129], off
	v_lshl_add_u64 v[2:3], v[2:3], 0, s[4:5]
	s_mov_b32 m0, s23
	s_nop 0
	global_load_lds_dwordx4 v[2:3], off
	s_waitcnt lgkmcnt(8)
	s_barrier
	s_waitcnt lgkmcnt(0)
	s_setprio 1
	s_waitcnt lgkmcnt(0)
	v_mfma_f32_16x16x32_bf16 v[52:55], v[108:111], v[124:127], v[52:55]
	v_mfma_f32_16x16x32_bf16 v[56:59], v[116:119], v[124:127], v[56:59]
	v_mfma_f32_16x16x32_bf16 v[60:63], v[108:111], v[164:167], v[60:63]
	v_mfma_f32_16x16x32_bf16 v[64:67], v[116:119], v[164:167], v[64:67]
	v_mfma_f32_16x16x32_bf16 v[68:71], v[108:111], v[172:175], v[68:71]
	v_mfma_f32_16x16x32_bf16 v[72:75], v[116:119], v[172:175], v[72:75]
	v_mfma_f32_16x16x32_bf16 v[76:79], v[108:111], v[180:183], v[76:79]
	v_mfma_f32_16x16x32_bf16 v[52:55], v[112:115], v[132:135], v[52:55]
	v_mfma_f32_16x16x32_bf16 v[56:59], v[120:123], v[132:135], v[56:59]
	v_mfma_f32_16x16x32_bf16 v[60:63], v[112:115], v[168:171], v[60:63]
	v_mfma_f32_16x16x32_bf16 v[64:67], v[120:123], v[168:171], v[64:67]
	v_mfma_f32_16x16x32_bf16 v[68:71], v[112:115], v[176:179], v[68:71]
	v_mfma_f32_16x16x32_bf16 v[72:75], v[120:123], v[176:179], v[72:75]
	v_mfma_f32_16x16x32_bf16 v[76:79], v[112:115], v[184:187], v[76:79]
	v_mfma_f32_16x16x32_bf16 v[80:83], v[116:119], v[180:183], v[80:83]
	v_mfma_f32_16x16x32_bf16 v[192:195], v[120:123], v[184:187], v[80:83]
	s_setprio 0
	s_barrier
	s_mov_b32 m0, s87
	v_lshl_add_u64 v[136:137], s[12:13], 0, v[0:1]
	s_mov_b64 s[4:5], 0x8000
	s_nop 1
	ds_read_b128 v[80:83], v189
	ds_read_b128 v[196:199], v189 offset:1024
	ds_read_b128 v[200:203], v189 offset:2048
	ds_read_b128 v[204:207], v189 offset:3072
	global_load_lds_dwordx4 v[136:137], off
	v_lshl_add_u64 v[2:3], v[136:137], 0, s[4:5]
	s_mov_b32 m0, s28
	s_nop 0
	global_load_lds_dwordx4 v[2:3], off
	s_barrier
; #define PG8_STAGE(bufoff, gbase, voff) do { _Pragma("unroll") for (int _i = 0; _i < 2; ++_i) \
;         __builtin_amdgcn_global_load_lds((const unsigned*)((const char*)(gbase) + (size_t)_i * vst##voff + v##voff), (LAS unsigned*)(lds + (bufoff) + ldsw + _i * 8192), 16, 0, 0); } while (0)
; #define PG8_LDA(dst, b, h) do { _Pragma("unroll") for (int m = 0; m < 4; ++m) _Pragma("unroll") for (int k = 0; k < 2; ++k) dst[m][k] = *(const LAS bf16x8*)(lds + PG8_SA(b, h) + aoff + m * 2048 + k * 1024); } while (0)
; #define PG8_LDB(dst, b, h) do { _Pragma("unroll") for (int n = 0; n < 2; ++n) _Pragma("unroll") for (int k = 0; k < 2; ++k) dst[n][k] = *(const LAS bf16x8*)(lds + PG8_SB(b, h) + boff + n * 2048 + k * 1024); } while (0)
; #define PG8_MMA(ai, bj, At, Bt) do { __builtin_amdgcn_s_setprio(1); _Pragma("unroll") for (int m = 0; m < 4; ++m) _Pragma("unroll") for (int n = 0; n < 2; ++n) _Pragma("unroll") for (int k = 0; k < 2; ++k) \
;         acc[ai][bj][m][n] = __builtin_amdgcn_mfma_f32_16x16x32_bf16(Bt[n][k], At[m][k], acc[ai][bj][m][n], 0, 0, 0); __builtin_amdgcn_s_setprio(0); } while (0)
; #define PG8_WAIT_V(n) asm volatile("s_waitcnt vmcnt(" #n ")" ::: "memory")
; #define PG8_WAIT_L(n) asm volatile("s_waitcnt lgkmcnt(" #n ")" ::: "memory")
; #define PG8_BAR __builtin_amdgcn_s_barrier()
; #define PG8_SCHED __builtin_amdgcn_sched_barrier(0)
; template <class Epi>
; DI void gemm_phase(LAS unsigned char* lds, const Gemm g, const StaticOrder& S, const Epi& E, const int tid) {
;     ...
;             PG8_BAR; PG8_WAIT_L(0); PG8_MMA(0, 1, At, B1); PG8_BAR;
;             PG8_LDA(At, 0, 1); PG8_STAGE(PG8_SA(0, 0), a2, offA);
;             PG8_BAR; PG8_WAIT_L(0); PG8_MMA(1, 0, At, B0); PG8_BAR; PG8_SCHED;
;             PG8_STAGE(PG8_SB(0, 1), b2 + hsB, offB);
;             PG8_WAIT_V(6); PG8_BAR; PG8_MMA(1, 1, At, B1); PG8_BAR;
;             PG8_LDB(B0, 1, 0); PG8_SCHED; PG8_LDA(At, 1, 0); PG8_STAGE(PG8_SA(0, 1), a2 + hsA, offA);
	s_waitcnt lgkmcnt(0)
	s_setprio 1
	s_waitcnt lgkmcnt(0)
	v_mfma_f32_16x16x32_bf16 v[20:23], v[200:203], v[124:127], v[20:23]
	v_mfma_f32_16x16x32_bf16 v[24:27], v[80:83], v[164:167], v[24:27]
	v_mfma_f32_16x16x32_bf16 v[28:31], v[200:203], v[164:167], v[28:31]
	v_mfma_f32_16x16x32_bf16 v[32:35], v[80:83], v[172:175], v[32:35]
	v_mfma_f32_16x16x32_bf16 v[36:39], v[200:203], v[172:175], v[36:39]
	v_mfma_f32_16x16x32_bf16 v[40:43], v[80:83], v[180:183], v[40:43]
	v_mfma_f32_16x16x32_bf16 v[44:47], v[200:203], v[180:183], v[44:47]
	v_mfma_f32_16x16x32_bf16 v[100:103], v[80:83], v[124:127], v[100:103]
	v_mfma_f32_16x16x32_bf16 v[20:23], v[204:207], v[132:135], v[20:23]
	v_mfma_f32_16x16x32_bf16 v[24:27], v[196:199], v[168:171], v[24:27]
	v_mfma_f32_16x16x32_bf16 v[28:31], v[204:207], v[168:171], v[28:31]
	v_mfma_f32_16x16x32_bf16 v[32:35], v[196:199], v[176:179], v[32:35]
	v_mfma_f32_16x16x32_bf16 v[36:39], v[204:207], v[176:179], v[36:39]
	v_mfma_f32_16x16x32_bf16 v[40:43], v[196:199], v[184:187], v[40:43]
	v_mfma_f32_16x16x32_bf16 v[44:47], v[204:207], v[184:187], v[44:47]
	v_mfma_f32_16x16x32_bf16 v[208:211], v[196:199], v[132:135], v[100:103]
	s_setprio 0
	s_mov_b32 m0, s40
	v_lshl_add_u64 v[250:251], s[24:25], 0, v[130:131]
	s_mov_b64 s[12:13], 0xd8000
	s_barrier
	ds_read_b128 v[100:103], v139 offset:16384
	ds_read_b128 v[124:127], v139 offset:17408
	ds_read_b128 v[132:135], v139 offset:18432
	ds_read_b128 v[164:167], v139 offset:19456
	ds_read_b128 v[168:171], v139 offset:20480
	ds_read_b128 v[172:175], v139 offset:21504
	ds_read_b128 v[176:179], v139 offset:22528
	ds_read_b128 v[180:183], v139 offset:23552
	global_load_lds_dwordx4 v[250:251], off
	v_lshl_add_u64 v[2:3], v[250:251], 0, s[12:13]
	s_mov_b32 m0, s41
	s_nop 0
	global_load_lds_dwordx4 v[2:3], off
	s_barrier
	s_waitcnt lgkmcnt(0)
	s_setprio 1
	s_waitcnt lgkmcnt(0)
	v_mfma_f32_16x16x32_bf16 v[144:147], v[116:119], v[100:103], v[144:147]
	v_mfma_f32_16x16x32_bf16 v[2:5], v[108:111], v[176:179], v[4:7]
	v_mfma_f32_16x16x32_bf16 v[140:143], v[108:111], v[100:103], v[140:143]
	v_mfma_f32_16x16x32_bf16 v[144:147], v[120:123], v[124:127], v[144:147]
	v_mfma_f32_16x16x32_bf16 v[148:151], v[108:111], v[132:135], v[148:151]
	v_mfma_f32_16x16x32_bf16 v[152:155], v[116:119], v[132:135], v[152:155]
	v_mfma_f32_16x16x32_bf16 v[156:159], v[108:111], v[168:171], v[156:159]
	v_mfma_f32_16x16x32_bf16 v[160:163], v[116:119], v[168:171], v[160:163]
	v_mfma_f32_16x16x32_bf16 v[2:5], v[112:115], v[180:183], v[2:5]
	v_mfma_f32_16x16x32_bf16 v[6:9], v[116:119], v[176:179], v[8:11]
	v_mfma_f32_16x16x32_bf16 v[140:143], v[112:115], v[124:127], v[140:143]
	v_mfma_f32_16x16x32_bf16 v[148:151], v[112:115], v[164:167], v[148:151]
	v_mfma_f32_16x16x32_bf16 v[152:155], v[120:123], v[164:167], v[152:155]
	v_mfma_f32_16x16x32_bf16 v[156:159], v[112:115], v[172:175], v[156:159]
	v_mfma_f32_16x16x32_bf16 v[160:163], v[120:123], v[172:175], v[160:163]
	v_mfma_f32_16x16x32_bf16 v[184:187], v[120:123], v[180:183], v[6:9]
	s_setprio 0
	s_barrier
	s_mov_b64 s[4:5], 0x10000
	s_mov_b32 m0, s30
	v_lshl_add_u64 v[6:7], v[136:137], 0, s[4:5]
	global_load_lds_dwordx4 v[6:7], off
	v_lshl_add_u64 v[6:7], v[136:137], 0, s[82:83]
	s_mov_b32 m0, s29
	s_nop 0
	global_load_lds_dwordx4 v[6:7], off
	s_waitcnt vmcnt(6)
	s_barrier
	s_setprio 1
	v_mfma_f32_16x16x32_bf16 v[6:9], v[80:83], v[100:103], v[12:15]
	v_mfma_f32_16x16x32_bf16 v[10:13], v[196:199], v[124:127], v[6:9]
	v_mfma_f32_16x16x32_bf16 v[6:9], v[200:203], v[100:103], v[16:19]
	v_mfma_f32_16x16x32_bf16 v[14:17], v[204:207], v[124:127], v[6:9]
	v_mfma_f32_16x16x32_bf16 v[6:9], v[80:83], v[132:135], v[48:51]
	v_mfma_f32_16x16x32_bf16 v[212:215], v[196:199], v[164:167], v[6:9]
	v_mfma_f32_16x16x32_bf16 v[6:9], v[200:203], v[132:135], v[92:95]
	v_mfma_f32_16x16x32_bf16 v[132:135], v[204:207], v[164:167], v[6:9]
	v_mfma_f32_16x16x32_bf16 v[6:9], v[80:83], v[168:171], v[96:99]
	v_mfma_f32_16x16x32_bf16 v[164:167], v[196:199], v[172:175], v[6:9]
	v_mfma_f32_16x16x32_bf16 v[6:9], v[200:203], v[168:171], v[104:107]
	v_mfma_f32_16x16x32_bf16 v[168:171], v[204:207], v[172:175], v[6:9]
	v_mfma_f32_16x16x32_bf16 v[6:9], v[80:83], v[176:179], v[84:87]
	v_mfma_f32_16x16x32_bf16 v[172:175], v[196:199], v[180:183], v[6:9]
	v_mfma_f32_16x16x32_bf16 v[6:9], v[200:203], v[176:179], v[88:91]
	v_mfma_f32_16x16x32_bf16 v[176:179], v[204:207], v[180:183], v[6:9]
	s_setprio 0
	s_barrier
	s_nop 4
	ds_read_b128 v[6:9], v190
	ds_read_b128 v[180:183], v190 offset:1024
	ds_read_b128 v[196:199], v190 offset:2048
	ds_read_b128 v[200:203], v190 offset:3072
	s_mov_b64 s[4:5], 0x1b0000
	s_mov_b32 m0, s42
	v_lshl_add_u64 v[18:19], v[250:251], 0, s[4:5]
	s_mov_b64 s[4:5], 0x288000
	ds_read_b128 v[90:93], v139 offset:32768
	ds_read_b128 v[94:97], v139 offset:33792
	ds_read_b128 v[106:109], v139 offset:34816
	ds_read_b128 v[204:207], v139 offset:35840
	ds_read_b128 v[216:219], v139 offset:36864
	ds_read_b128 v[230:233], v139 offset:37888
	ds_read_b128 v[234:237], v139 offset:38912
	ds_read_b128 v[238:241], v139 offset:39936
	global_load_lds_dwordx4 v[18:19], off
	v_lshl_add_u64 v[18:19], v[250:251], 0, s[4:5]
	s_mov_b32 m0, s43
	s_nop 0
	global_load_lds_dwordx4 v[18:19], off
	s_waitcnt lgkmcnt(8)
	s_barrier
; #define PG8_STAGE(bufoff, gbase, voff) do { _Pragma("unroll") for (int _i = 0; _i < 2; ++_i) \
;         __builtin_amdgcn_global_load_lds((const unsigned*)((const char*)(gbase) + (size_t)_i * vst##voff + v##voff), (LAS unsigned*)(lds + (bufoff) + ldsw + _i * 8192), 16, 0, 0); } while (0)
; #define PG8_LDA(dst, b, h) do { _Pragma("unroll") for (int m = 0; m < 4; ++m) _Pragma("unroll") for (int k = 0; k < 2; ++k) dst[m][k] = *(const LAS bf16x8*)(lds + PG8_SA(b, h) + aoff + m * 2048 + k * 1024); } while (0)
; #define PG8_LDB(dst, b, h) do { _Pragma("unroll") for (int n = 0; n < 2; ++n) _Pragma("unroll") for (int k = 0; k < 2; ++k) dst[n][k] = *(const LAS bf16x8*)(lds + PG8_SB(b, h) + boff + n * 2048 + k * 1024); } while (0)
; #define PG8_MMA(ai, bj, At, Bt) do { __builtin_amdgcn_s_setprio(1); _Pragma("unroll") for (int m = 0; m < 4; ++m) _Pragma("unroll") for (int n = 0; n < 2; ++n) _Pragma("unroll") for (int k = 0; k < 2; ++k) \
;         acc[ai][bj][m][n] = __builtin_amdgcn_mfma_f32_16x16x32_bf16(Bt[n][k], At[m][k], acc[ai][bj][m][n], 0, 0, 0); __builtin_amdgcn_s_setprio(0); } while (0)
; #define PG8_WAIT_L(n) asm volatile("s_waitcnt lgkmcnt(" #n ")" ::: "memory")
; #define PG8_BAR __builtin_amdgcn_s_barrier()
; #define PG8_SCHED __builtin_amdgcn_sched_barrier(0)
; template <class Epi>
; DI void gemm_phase(LAS unsigned char* lds, const Gemm g, const StaticOrder& S, const Epi& E, const int tid) {
;     ...
;             PG8_WAIT_L(8); PG8_BAR; PG8_WAIT_L(0); PG8_MMA(0, 0, At, B0); PG8_BAR; PG8_SCHED;
;             PG8_LDB(B1, 1, 1); PG8_STAGE(PG8_SB(1, 0), b3, offB);
;             PG8_BAR; PG8_WAIT_L(0); PG8_MMA(0, 1, At, B1); PG8_BAR;
;             PG8_LDA(At, 1, 1); PG8_STAGE(PG8_SA(1, 0), a3, offA);
	s_waitcnt lgkmcnt(0)
	s_setprio 1
	s_waitcnt lgkmcnt(0)
	v_mfma_f32_16x16x32_bf16 v[48:51], v[6:9], v[90:93], v[52:55]
	v_mfma_f32_16x16x32_bf16 v[118:121], v[180:183], v[94:97], v[48:51]
	v_mfma_f32_16x16x32_bf16 v[48:51], v[196:199], v[90:93], v[56:59]
	v_mfma_f32_16x16x32_bf16 v[114:117], v[200:203], v[94:97], v[48:51]
	v_mfma_f32_16x16x32_bf16 v[48:51], v[6:9], v[106:109], v[60:63]
	v_mfma_f32_16x16x32_bf16 v[102:105], v[180:183], v[204:207], v[48:51]
	v_mfma_f32_16x16x32_bf16 v[48:51], v[196:199], v[106:109], v[64:67]
	v_mfma_f32_16x16x32_bf16 v[98:101], v[200:203], v[204:207], v[48:51]
	v_mfma_f32_16x16x32_bf16 v[48:51], v[6:9], v[216:219], v[68:71]
	v_mfma_f32_16x16x32_bf16 v[86:89], v[180:183], v[230:233], v[48:51]
	v_mfma_f32_16x16x32_bf16 v[48:51], v[196:199], v[216:219], v[72:75]
	v_mfma_f32_16x16x32_bf16 v[82:85], v[200:203], v[230:233], v[48:51]
	v_mfma_f32_16x16x32_bf16 v[48:51], v[6:9], v[234:237], v[76:79]
	v_mfma_f32_16x16x32_bf16 v[54:57], v[180:183], v[238:241], v[48:51]
	v_mfma_f32_16x16x32_bf16 v[48:51], v[196:199], v[234:237], v[192:195]
	v_mfma_f32_16x16x32_bf16 v[50:53], v[200:203], v[238:241], v[48:51]
	s_setprio 0
	s_barrier
	s_mov_b32 m0, vcc_lo
	v_lshl_add_u64 v[18:19], v[136:137], 0, s[88:89]
	s_mov_b64 s[4:5], 0x8080
	ds_read_b128 v[192:195], v191
	ds_read_b128 v[242:245], v191 offset:1024
	ds_read_b128 v[246:249], v191 offset:2048
	ds_read_b128 v[188:191], v191 offset:3072
	global_load_lds_dwordx4 v[18:19], off
	v_lshl_add_u64 v[18:19], v[136:137], 0, s[4:5]
	s_mov_b32 m0, s6
	s_nop 0
	global_load_lds_dwordx4 v[18:19], off
	s_barrier
	s_waitcnt lgkmcnt(0)
	s_setprio 1
	s_waitcnt lgkmcnt(0)
	v_mfma_f32_16x16x32_bf16 v[18:21], v[246:249], v[90:93], v[20:23]
	v_mfma_f32_16x16x32_bf16 v[122:125], v[188:191], v[94:97], v[18:21]
	v_mfma_f32_16x16x32_bf16 v[18:21], v[192:195], v[106:109], v[24:27]
	v_mfma_f32_16x16x32_bf16 v[110:113], v[242:245], v[204:207], v[18:21]
	v_mfma_f32_16x16x32_bf16 v[18:21], v[246:249], v[106:109], v[28:31]
	v_mfma_f32_16x16x32_bf16 v[58:61], v[192:195], v[90:93], v[208:211]
	v_mfma_f32_16x16x32_bf16 v[106:109], v[188:191], v[204:207], v[18:21]
	v_mfma_f32_16x16x32_bf16 v[18:21], v[192:195], v[216:219], v[32:35]
	v_mfma_f32_16x16x32_bf16 v[126:129], v[242:245], v[94:97], v[58:61]
	v_mfma_f32_16x16x32_bf16 v[94:97], v[242:245], v[230:233], v[18:21]
	v_mfma_f32_16x16x32_bf16 v[18:21], v[246:249], v[216:219], v[36:39]
	v_mfma_f32_16x16x32_bf16 v[90:93], v[188:191], v[230:233], v[18:21]
	v_mfma_f32_16x16x32_bf16 v[18:21], v[192:195], v[234:237], v[40:43]
	v_mfma_f32_16x16x32_bf16 v[74:77], v[242:245], v[238:241], v[18:21]
	v_mfma_f32_16x16x32_bf16 v[18:21], v[246:249], v[234:237], v[44:47]
	v_mfma_f32_16x16x32_bf16 v[66:69], v[188:191], v[238:241], v[18:21]
	s_setprio 0
	s_mov_b32 m0, s47
	s_nop 4
	v_lshl_add_u64 v[18:19], v[250:251], 0, s[88:89]
	s_mov_b64 s[6:7], 0xd8080
	s_barrier
	ds_read_b128 v[26:29], v139 offset:49152
	ds_read_b128 v[30:33], v139 offset:50176
	ds_read_b128 v[42:45], v139 offset:51200
	ds_read_b128 v[204:207], v139 offset:52224
	ds_read_b128 v[208:211], v139 offset:53248
	ds_read_b128 v[216:219], v139 offset:54272
	ds_read_b128 v[230:233], v139 offset:55296
	ds_read_b128 v[234:237], v139 offset:56320
	global_load_lds_dwordx4 v[18:19], off
	v_lshl_add_u64 v[18:19], v[250:251], 0, s[6:7]
	s_mov_b32 m0, s58
	s_nop 0
	global_load_lds_dwordx4 v[18:19], off
	s_barrier
; #define PG8_STAGE(bufoff, gbase, voff) do { _Pragma("unroll") for (int _i = 0; _i < 2; ++_i) \
;         __builtin_amdgcn_global_load_lds((const unsigned*)((const char*)(gbase) + (size_t)_i * vst##voff + v##voff), (LAS unsigned*)(lds + (bufoff) + ldsw + _i * 8192), 16, 0, 0); } while (0)
; #define PG8_MMA(ai, bj, At, Bt) do { __builtin_amdgcn_s_setprio(1); _Pragma("unroll") for (int m = 0; m < 4; ++m) _Pragma("unroll") for (int n = 0; n < 2; ++n) _Pragma("unroll") for (int k = 0; k < 2; ++k) \
;         acc[ai][bj][m][n] = __builtin_amdgcn_mfma_f32_16x16x32_bf16(Bt[n][k], At[m][k], acc[ai][bj][m][n], 0, 0, 0); __builtin_amdgcn_s_setprio(0); } while (0)
; #define PG8_WAIT_V(n) asm volatile("s_waitcnt vmcnt(" #n ")" ::: "memory")
; #define PG8_WAIT_L(n) asm volatile("s_waitcnt lgkmcnt(" #n ")" ::: "memory")
; #define PG8_BAR __builtin_amdgcn_s_barrier()
; #define PG8_SCHED __builtin_amdgcn_sched_barrier(0)
; template <class Epi>
; DI void gemm_phase(LAS unsigned char* lds, const Gemm g, const StaticOrder& S, const Epi& E, const int tid) {
;     ...
;             PG8_BAR; PG8_WAIT_L(0); PG8_MMA(1, 0, At, B0); PG8_BAR; PG8_SCHED;
;             PG8_STAGE(PG8_SB(1, 1), b3 + hsB, offB);
;             PG8_WAIT_V(6); PG8_BAR; PG8_MMA(1, 1, At, B1); PG8_BAR;
;     DI void operator()(const AccT& acc, const Unit& u, int wr, int wc, int fr, int fq) const {
;         float sv_[2][4];
; #pragma unroll
;         for (int ai = 0; ai < 2; ++ai)
; #pragma unroll
;             for (int m = 0; m < 4; ++m) sv_[ai][m] = st ? st[u.pm * 256 + ai * 128 + wr * 64 + m * 16 + fr] : 0.f;
	s_waitcnt lgkmcnt(0)
	s_setprio 1
	s_waitcnt lgkmcnt(0)
	v_mfma_f32_16x16x32_bf16 v[18:21], v[6:9], v[26:29], v[140:143]
	v_mfma_f32_16x16x32_bf16 v[62:65], v[180:183], v[30:33], v[18:21]
	v_mfma_f32_16x16x32_bf16 v[18:21], v[196:199], v[26:29], v[144:147]
	v_mfma_f32_16x16x32_bf16 v[58:61], v[200:203], v[30:33], v[18:21]
	v_mfma_f32_16x16x32_bf16 v[18:21], v[6:9], v[42:45], v[148:151]
	v_mfma_f32_16x16x32_bf16 v[38:41], v[180:183], v[204:207], v[18:21]
	v_mfma_f32_16x16x32_bf16 v[18:21], v[196:199], v[42:45], v[152:155]
	v_mfma_f32_16x16x32_bf16 v[34:37], v[200:203], v[204:207], v[18:21]
	v_mfma_f32_16x16x32_bf16 v[18:21], v[6:9], v[208:211], v[156:159]
	v_mfma_f32_16x16x32_bf16 v[2:5], v[6:9], v[230:233], v[2:5]
	v_mfma_f32_16x16x32_bf16 v[22:25], v[180:183], v[216:219], v[18:21]
	v_mfma_f32_16x16x32_bf16 v[18:21], v[196:199], v[208:211], v[160:163]
	v_mfma_f32_16x16x32_bf16 v[6:9], v[180:183], v[234:237], v[2:5]
	v_mfma_f32_16x16x32_bf16 v[2:5], v[196:199], v[230:233], v[184:187]
	v_mfma_f32_16x16x32_bf16 v[18:21], v[200:203], v[216:219], v[18:21]
	v_mfma_f32_16x16x32_bf16 v[2:5], v[200:203], v[234:237], v[2:5]
	s_setprio 0
	s_barrier
	s_mov_b64 s[4:5], 0x10080
	s_mov_b32 m0, vcc_hi
	v_lshl_add_u64 v[46:47], v[136:137], 0, s[4:5]
	global_load_lds_dwordx4 v[46:47], off
	v_lshl_add_u64 v[46:47], v[136:137], 0, s[2:3]
	s_mov_b32 m0, s36
	s_nop 0
	global_load_lds_dwordx4 v[46:47], off
	s_waitcnt vmcnt(6)
	s_barrier
	s_setprio 1
	v_mfma_f32_16x16x32_bf16 v[10:13], v[192:195], v[26:29], v[10:13]
	v_mfma_f32_16x16x32_bf16 v[78:81], v[242:245], v[30:33], v[10:13]
	v_mfma_f32_16x16x32_bf16 v[10:13], v[246:249], v[26:29], v[14:17]
	v_mfma_f32_16x16x32_bf16 v[70:73], v[188:191], v[30:33], v[10:13]
	v_mfma_f32_16x16x32_bf16 v[10:13], v[192:195], v[42:45], v[212:215]
	v_mfma_f32_16x16x32_bf16 v[46:49], v[242:245], v[204:207], v[10:13]
	v_mfma_f32_16x16x32_bf16 v[10:13], v[246:249], v[42:45], v[132:135]
	v_mfma_f32_16x16x32_bf16 v[42:45], v[188:191], v[204:207], v[10:13]
	v_mfma_f32_16x16x32_bf16 v[10:13], v[192:195], v[208:211], v[164:167]
	v_mfma_f32_16x16x32_bf16 v[30:33], v[242:245], v[216:219], v[10:13]
	v_mfma_f32_16x16x32_bf16 v[10:13], v[246:249], v[208:211], v[168:171]
	v_mfma_f32_16x16x32_bf16 v[26:29], v[188:191], v[216:219], v[10:13]
	v_mfma_f32_16x16x32_bf16 v[10:13], v[192:195], v[230:233], v[172:175]
	v_mfma_f32_16x16x32_bf16 v[14:17], v[242:245], v[234:237], v[10:13]
	v_mfma_f32_16x16x32_bf16 v[10:13], v[246:249], v[230:233], v[176:179]
	v_mfma_f32_16x16x32_bf16 v[10:13], v[188:191], v[234:237], v[10:13]
	s_setprio 0
	s_lshl_b32 s6, s86, 8
	s_add_i32 s6, s6, s46
	s_barrier
	v_mbcnt_lo_u32_b32 v136, -1, 0
	v_mbcnt_hi_u32_b32 v136, -1, v136
	v_and_or_b32 v132, v136, 15, s6
	v_ashrrev_i32_e32 v133, 31, v132
	v_mov_b32_e32 v137, 0x358637bd
	v_mov_b32_e32 v146, 0x358637bd
	v_mov_b32_e32 v145, 0x358637bd
	v_mov_b32_e32 v144, 0x358637bd
	v_mov_b32_e32 v143, 0x358637bd
	v_mov_b32_e32 v142, 0x358637bd
	v_mov_b32_e32 v141, 0x358637bd
	v_mov_b32_e32 v140, 0x358637bd
	s_mov_b64 s[4:5], 0xb0000
	s_mov_b64 s[12:13], -1
	s_andn2_b64 vcc, exec, s[18:19]
	s_cbranch_vccnz .LBB0_1109
	v_lshl_add_u64 v[134:135], v[132:133], 2, s[8:9]
	global_load_dword v137, v[134:135], off
	global_load_dword v146, v[134:135], off offset:64
	global_load_dword v145, v[134:135], off offset:128
	global_load_dword v144, v[134:135], off offset:192
	global_load_dword v143, v[134:135], off offset:512
	global_load_dword v142, v[134:135], off offset:576
	global_load_dword v141, v[134:135], off offset:640
	global_load_dword v140, v[134:135], off offset:704
	s_waitcnt vmcnt(0)
	v_fmamk_f32 v137, v137, 0x3b800000, v225
	v_fmamk_f32 v146, v146, 0x3b800000, v225
	v_fmamk_f32 v145, v145, 0x3b800000, v225
	v_fmamk_f32 v144, v144, 0x3b800000, v225
	v_fmamk_f32 v143, v143, 0x3b800000, v225
	v_fmamk_f32 v142, v142, 0x3b800000, v225
	v_fmamk_f32 v141, v141, 0x3b800000, v225
	v_fmamk_f32 v140, v140, 0x3b800000, v225
	s_branch .LBB0_1109

; __global__ void __launch_bounds__(512, 2) fwd_mega(Params P) {
;     ...
;                 attn_unit<192, true>(lds, WSB(WS_QS) + (size_t)b * TS * 1536 + hh * 192, 1536, TS, WSB(WS_KNS) + (size_t)b * KPAD * 1024 + hh * 128, 1024, WSB(WS_KRALL) + (size_t)b * KPAD * 64,
;                                      WSB(WS_VTS) + ((size_t)b * 1024 + hh * 128) * KPAD, KPAD, 17, wid == 0 ? 17 : 0, KALL,
;                                      WSB(WS_OMS) + (size_t)b * TS * 1024 + hh * 128, 1024, tid, wid, lane);
.LBB0_1534:
	v_lshl_add_u64 v[2:3], s[8:9], 0, v[200:201]
	v_add_co_u32_e32 v8, vcc, 0x2df62000, v2
	v_lshl_add_u64 v[6:7], s[8:9], 0, v[184:185]
	s_nop 0
	v_addc_co_u32_e32 v9, vcc, 0, v3, vcc
	global_load_dwordx4 v[2:5], v[8:9], off offset:2176
	global_load_dwordx4 v[10:13], v[8:9], off offset:2048
	s_nop 0
	global_load_dwordx4 v[6:9], v[6:7], off
	s_and_b32 s17, s46, 1
	s_mul_i32 s14, s17, 0xa800
	s_add_i32 s16, s14, 0
	s_cmp_lt_u32 s46, 17
	s_cselect_b64 s[14:15], -1, 0
	s_and_b64 s[62:63], s[94:95], s[14:15]
	v_cndmask_b32_e64 v0, 0, 1, s[62:63]
	v_cmp_ne_u32_e64 s[14:15], 1, v0
	s_andn2_b64 vcc, exec, s[62:63]
	s_cbranch_vccnz .LBB0_1536
	v_add3_u32 v0, s16, v207, v177
	ds_read_b128 v[80:83], v0
	ds_read_b128 v[96:99], v0 offset:12800
	ds_read_b128 v[186:189], v0 offset:32
	ds_read_b128 v[190:193], v0 offset:12832
	ds_read_b128 v[194:197], v0 offset:64
	ds_read_b128 v[230:233], v0 offset:12864
	ds_read_b128 v[234:237], v0 offset:96
	ds_read_b128 v[212:215], v0 offset:12896
	s_waitcnt lgkmcnt(7)
	v_mfma_f32_32x32x16_bf16 v[80:95], v[80:83], v[124:127], 0
	s_waitcnt lgkmcnt(6)
	v_mfma_f32_32x32x16_bf16 v[96:111], v[96:99], v[124:127], 0
	s_waitcnt lgkmcnt(5)
	v_mfma_f32_32x32x16_bf16 v[80:95], v[186:189], v[112:115], v[80:95]
	ds_read_b128 v[186:189], v0 offset:128
	s_waitcnt lgkmcnt(5)
	v_mfma_f32_32x32x16_bf16 v[96:111], v[190:193], v[112:115], v[96:111]
	ds_read_b128 v[190:193], v0 offset:12928
	s_waitcnt lgkmcnt(5)
	v_mfma_f32_32x32x16_bf16 v[80:95], v[194:197], v[140:143], v[80:95]
	ds_read_b128 v[194:197], v0 offset:160
	s_waitcnt lgkmcnt(5)
	v_mfma_f32_32x32x16_bf16 v[96:111], v[230:233], v[140:143], v[96:111]
	ds_read_b128 v[230:233], v0 offset:12960
	s_waitcnt lgkmcnt(5)
	v_mfma_f32_32x32x16_bf16 v[80:95], v[234:237], v[120:123], v[80:95]
	ds_read_b128 v[234:237], v0 offset:192
	s_waitcnt lgkmcnt(5)
	v_mfma_f32_32x32x16_bf16 v[96:111], v[212:215], v[120:123], v[96:111]
	ds_read_b128 v[212:215], v0 offset:12992
	s_waitcnt lgkmcnt(5)
	v_mfma_f32_32x32x16_bf16 v[80:95], v[186:189], v[148:151], v[80:95]
	ds_read_b128 v[186:189], v0 offset:224
	s_waitcnt lgkmcnt(5)
	v_mfma_f32_32x32x16_bf16 v[96:111], v[190:193], v[148:151], v[96:111]
	ds_read_b128 v[190:193], v0 offset:13024
	s_waitcnt lgkmcnt(5)
	v_mfma_f32_32x32x16_bf16 v[80:95], v[194:197], v[132:135], v[80:95]
	ds_read_b128 v[194:197], v0 offset:256
	s_waitcnt lgkmcnt(5)
	v_mfma_f32_32x32x16_bf16 v[96:111], v[230:233], v[132:135], v[96:111]
	ds_read_b128 v[230:233], v0 offset:13056
	s_waitcnt lgkmcnt(5)
	v_mfma_f32_32x32x16_bf16 v[80:95], v[234:237], v[152:155], v[80:95]
	ds_read_b128 v[234:237], v0 offset:288
	s_waitcnt lgkmcnt(5)
	v_mfma_f32_32x32x16_bf16 v[96:111], v[212:215], v[152:155], v[96:111]
	ds_read_b128 v[212:215], v0 offset:13088
	s_waitcnt lgkmcnt(5)
	v_mfma_f32_32x32x16_bf16 v[80:95], v[186:189], v[144:147], v[80:95]
	ds_read_b128 v[186:189], v0 offset:320
	s_waitcnt lgkmcnt(5)
	v_mfma_f32_32x32x16_bf16 v[96:111], v[190:193], v[144:147], v[96:111]
	ds_read_b128 v[190:193], v0 offset:13120
	s_waitcnt lgkmcnt(5)
	v_mfma_f32_32x32x16_bf16 v[80:95], v[194:197], v[156:159], v[80:95]
	ds_read_b128 v[194:197], v0 offset:352
	s_waitcnt lgkmcnt(5)
	v_mfma_f32_32x32x16_bf16 v[96:111], v[230:233], v[156:159], v[96:111]
	ds_read_b128 v[230:233], v0 offset:13152
	s_waitcnt lgkmcnt(5)
	v_mfma_f32_32x32x16_bf16 v[80:95], v[234:237], v[116:119], v[80:95]
	s_waitcnt lgkmcnt(4)
	v_mfma_f32_32x32x16_bf16 v[96:111], v[212:215], v[116:119], v[96:111]
	s_waitcnt lgkmcnt(3)
	v_mfma_f32_32x32x16_bf16 v[80:95], v[186:189], v[136:139], v[80:95]
	s_waitcnt lgkmcnt(2)
	v_mfma_f32_32x32x16_bf16 v[96:111], v[190:193], v[136:139], v[96:111]
	s_waitcnt lgkmcnt(1)
	v_mfma_f32_32x32x16_bf16 v[80:95], v[194:197], v[128:131], v[80:95]
	s_waitcnt lgkmcnt(0)
	v_mfma_f32_32x32x16_bf16 v[96:111], v[230:233], v[128:131], v[96:111]

; template <class Epi>
; DI void gemm_phase(LAS unsigned char* lds, const Gemm g, const StaticOrder& S, const Epi& E, const int tid) {
;     ...
; #pragma unroll
;         for (int a = 0; a < 2; ++a)
; #pragma unroll
;             for (int b = 0; b < 2; ++b)
; #pragma unroll
;                 for (int m = 0; m < 4; ++m)
; #pragma unroll
;                     for (int n = 0; n < 2; ++n) acc[a][b][m][n] = (f32x4){0.f, 0.f, 0.f, 0.f};
;         cur = nxt; cA = nA; cB = nB; ++ui;
;     DI void operator()(const AccT& acc, const Unit& u, int wr, int wc, int fr, int fq) const {
;         float sv_[2][4];
; #pragma unroll
;         for (int ai = 0; ai < 2; ++ai)
; #pragma unroll
;             for (int m = 0; m < 4; ++m) sv_[ai][m] = sh[u.pm * 256 + ai * 128 + wr * 64 + m * 16 + fr];
.LBB0_1785:
	v_mov_b64_e32 v[2:3], 0x580
	s_ashr_i32 s15, s14, 31
	v_cmp_lt_i64_e32 vcc, s[16:17], v[2:3]
	s_lshl_b64 s[16:17], s[14:15], 19
	s_add_u32 s16, s21, s16
	s_addc_u32 s17, s26, s17
	s_and_b64 s[18:19], vcc, exec
	s_cselect_b32 s15, s17, s23
	s_cselect_b32 s43, s16, s22
	s_ashr_i32 s11, s10, 31
	s_lshl_b64 s[18:19], s[10:11], 19
	s_add_u32 s18, s27, s18
	s_addc_u32 s19, s28, s19
	s_and_b64 s[46:47], vcc, exec
	s_cselect_b32 s11, s19, s25
	s_cselect_b32 s46, s18, s24
	s_add_u32 s22, s22, 0x40080
	s_addc_u32 s23, s23, 0
	s_add_u32 s24, s24, 0x100
	v_mov_b32_e32 v2, 0
	s_addc_u32 s25, s25, 0
	s_mov_b32 s47, -2
	v_mov_b32_e32 v3, v2
	v_mov_b32_e32 v4, v2
	v_mov_b32_e32 v5, v2
	v_mov_b32_e32 v6, v2
	v_mov_b32_e32 v7, v2
	v_mov_b32_e32 v8, v2
	v_mov_b32_e32 v9, v2
	v_mov_b32_e32 v18, v2
	v_mov_b32_e32 v19, v2
	v_mov_b32_e32 v20, v2
	v_mov_b32_e32 v21, v2
	v_mov_b32_e32 v22, v2
	v_mov_b32_e32 v23, v2
	v_mov_b32_e32 v24, v2
	v_mov_b32_e32 v25, v2
	v_mov_b32_e32 v34, v2
	v_mov_b32_e32 v35, v2
	v_mov_b32_e32 v36, v2
	v_mov_b32_e32 v37, v2
	v_mov_b32_e32 v38, v2
	v_mov_b32_e32 v39, v2
	v_mov_b32_e32 v40, v2
	v_mov_b32_e32 v41, v2
	v_mov_b32_e32 v50, v2
	v_mov_b32_e32 v51, v2
	v_mov_b32_e32 v52, v2
	v_mov_b32_e32 v53, v2
	v_mov_b32_e32 v54, v2
	v_mov_b32_e32 v55, v2
	v_mov_b32_e32 v56, v2
	v_mov_b32_e32 v57, v2
	v_mov_b32_e32 v10, v2
	v_mov_b32_e32 v11, v2
	v_mov_b32_e32 v12, v2
	v_mov_b32_e32 v13, v2
	v_mov_b32_e32 v14, v2
	v_mov_b32_e32 v15, v2
	v_mov_b32_e32 v16, v2
	v_mov_b32_e32 v17, v2
	v_mov_b32_e32 v26, v2
	v_mov_b32_e32 v27, v2
	v_mov_b32_e32 v28, v2
	v_mov_b32_e32 v29, v2
	v_mov_b32_e32 v30, v2
	v_mov_b32_e32 v31, v2
	v_mov_b32_e32 v32, v2
	v_mov_b32_e32 v33, v2
	v_mov_b32_e32 v42, v2
	v_mov_b32_e32 v43, v2
	v_mov_b32_e32 v44, v2
	v_mov_b32_e32 v45, v2
	v_mov_b32_e32 v46, v2
	v_mov_b32_e32 v47, v2
	v_mov_b32_e32 v48, v2
	v_mov_b32_e32 v49, v2
	v_mov_b32_e32 v58, v2
	v_mov_b32_e32 v59, v2
	v_mov_b32_e32 v60, v2
	v_mov_b32_e32 v61, v2
	v_mov_b32_e32 v62, v2
	v_mov_b32_e32 v63, v2
	v_mov_b32_e32 v64, v2
	v_mov_b32_e32 v65, v2
	v_mov_b32_e32 v66, v2
	v_mov_b32_e32 v67, v2
	v_mov_b32_e32 v68, v2
	v_mov_b32_e32 v69, v2
	v_mov_b32_e32 v70, v2
	v_mov_b32_e32 v71, v2
	v_mov_b32_e32 v72, v2
	v_mov_b32_e32 v73, v2
	v_mov_b32_e32 v82, v2
	v_mov_b32_e32 v83, v2
	v_mov_b32_e32 v84, v2
	v_mov_b32_e32 v85, v2
	v_mov_b32_e32 v86, v2
	v_mov_b32_e32 v87, v2
	v_mov_b32_e32 v88, v2
	v_mov_b32_e32 v89, v2
	v_mov_b32_e32 v98, v2
	v_mov_b32_e32 v99, v2
	v_mov_b32_e32 v100, v2
	v_mov_b32_e32 v101, v2
	v_mov_b32_e32 v102, v2
	v_mov_b32_e32 v103, v2
	v_mov_b32_e32 v104, v2
	v_mov_b32_e32 v105, v2
	v_mov_b32_e32 v114, v2
	v_mov_b32_e32 v115, v2
	v_mov_b32_e32 v116, v2
	v_mov_b32_e32 v117, v2
	v_mov_b32_e32 v118, v2
	v_mov_b32_e32 v119, v2
	v_mov_b32_e32 v120, v2
	v_mov_b32_e32 v121, v2
	v_mov_b32_e32 v74, v2
	v_mov_b32_e32 v75, v2
	v_mov_b32_e32 v76, v2
	v_mov_b32_e32 v77, v2
	v_mov_b32_e32 v78, v2
	v_mov_b32_e32 v79, v2
	v_mov_b32_e32 v80, v2
	v_mov_b32_e32 v81, v2
	v_mov_b32_e32 v90, v2
	v_mov_b32_e32 v91, v2
	v_mov_b32_e32 v92, v2
	v_mov_b32_e32 v93, v2
	v_mov_b32_e32 v94, v2
	v_mov_b32_e32 v95, v2
	v_mov_b32_e32 v96, v2
	v_mov_b32_e32 v97, v2
	v_mov_b32_e32 v106, v2
	v_mov_b32_e32 v107, v2
	v_mov_b32_e32 v108, v2
	v_mov_b32_e32 v109, v2
	v_mov_b32_e32 v110, v2
	v_mov_b32_e32 v111, v2
	v_mov_b32_e32 v112, v2
	v_mov_b32_e32 v113, v2
	v_mov_b32_e32 v122, v2
	v_mov_b32_e32 v123, v2
	v_mov_b32_e32 v124, v2
	v_mov_b32_e32 v125, v2
	v_mov_b32_e32 v126, v2
	v_mov_b32_e32 v127, v2
	v_mov_b32_e32 v128, v2
	v_mov_b32_e32 v129, v2
	v_mbcnt_lo_u32_b32 v240, -1, 0
	v_mbcnt_hi_u32_b32 v240, -1, v240
	v_and_b32_e32 v240, 15, v240
	v_lshl_or_b32 v240, s42, 8, v240
	v_add_u32_e32 v240, s36, v240
	v_mov_b32_e32 v241, 0
	v_lshl_add_u64 v[240:241], v[240:241], 2, s[8:9]
	global_load_dword v242, v[240:241], off
	global_load_dword v243, v[240:241], off offset:64
	global_load_dword v244, v[240:241], off offset:128
	global_load_dword v245, v[240:241], off offset:192
	global_load_dword v246, v[240:241], off offset:512
	global_load_dword v247, v[240:241], off offset:576
	global_load_dword v248, v[240:241], off offset:640
	global_load_dword v249, v[240:241], off offset:704
.LBB0_1786:
	s_add_u32 s58, s22, 0xfffc0080
	s_addc_u32 s59, s23, -1
	s_add_i32 s64, 0, 0x10000
	v_add_u32_e32 v134, s64, v137
	ds_read_b128 v[140:143], v134
	ds_read_b128 v[144:147], v134 offset:1024
	ds_read_b128 v[148:151], v134 offset:2048
	ds_read_b128 v[152:155], v134 offset:3072
	s_cmp_eq_u32 s47, 12
	s_cselect_b32 s59, s15, s59
	s_cselect_b32 s58, s43, s58
	s_cselect_b32 s63, s11, s25
	s_cselect_b32 s62, s46, s24
	v_lshl_add_u64 v[134:135], s[22:23], 0, v[132:133]
	s_add_i32 m0, s30, 0xc000
	ds_read_b128 v[156:159], v138
	ds_read_b128 v[160:163], v138 offset:1024
	ds_read_b128 v[164:167], v138 offset:2048
	ds_read_b128 v[168:171], v138 offset:3072
	ds_read_b128 v[172:175], v138 offset:4096
	ds_read_b128 v[176:179], v138 offset:5120
	ds_read_b128 v[180:183], v138 offset:6144
	ds_read_b128 v[184:187], v138 offset:7168
	global_load_lds_dwordx4 v[134:135], off
	v_lshl_add_u64 v[134:135], v[134:135], 0, s[56:57]
	s_add_i32 m0, s30, 0xe000
	s_nop 0
	global_load_lds_dwordx4 v[134:135], off
	s_waitcnt lgkmcnt(8)
	s_barrier
; #define PG8_STAGE(bufoff, gbase, voff) do { _Pragma("unroll") for (int _i = 0; _i < 2; ++_i) \
;         __builtin_amdgcn_global_load_lds((const unsigned*)((const char*)(gbase) + (size_t)_i * vst##voff + v##voff), (LAS unsigned*)(lds + (bufoff) + ldsw + _i * 8192), 16, 0, 0); } while (0)
; #define PG8_LDA(dst, b, h) do { _Pragma("unroll") for (int m = 0; m < 4; ++m) _Pragma("unroll") for (int k = 0; k < 2; ++k) dst[m][k] = *(const LAS bf16x8*)(lds + PG8_SA(b, h) + aoff + m * 2048 + k * 1024); } while (0)
; #define PG8_LDB(dst, b, h) do { _Pragma("unroll") for (int n = 0; n < 2; ++n) _Pragma("unroll") for (int k = 0; k < 2; ++k) dst[n][k] = *(const LAS bf16x8*)(lds + PG8_SB(b, h) + boff + n * 2048 + k * 1024); } while (0)
; #define PG8_MMA(ai, bj, At, Bt) do { __builtin_amdgcn_s_setprio(1); _Pragma("unroll") for (int m = 0; m < 4; ++m) _Pragma("unroll") for (int n = 0; n < 2; ++n) _Pragma("unroll") for (int k = 0; k < 2; ++k) \
;         acc[ai][bj][m][n] = __builtin_amdgcn_mfma_f32_16x16x32_bf16(Bt[n][k], At[m][k], acc[ai][bj][m][n], 0, 0, 0); __builtin_amdgcn_s_setprio(0); } while (0)
; #define PG8_WAIT_V(n) asm volatile("s_waitcnt vmcnt(" #n ")" ::: "memory")
; #define PG8_WAIT_L(n) asm volatile("s_waitcnt lgkmcnt(" #n ")" ::: "memory")
; #define PG8_BAR __builtin_amdgcn_s_barrier()
; #define PG8_SCHED __builtin_amdgcn_sched_barrier(0)
; template <class Epi>
; DI void gemm_phase(LAS unsigned char* lds, const Gemm g, const StaticOrder& S, const Epi& E, const int tid) {
;     ...
;             PG8_WAIT_L(8); PG8_BAR; PG8_WAIT_L(0); PG8_MMA(0, 0, At, B0); PG8_BAR; PG8_SCHED;
;             PG8_LDB(B1, 0, 1); PG8_STAGE(PG8_SB(0, 0), b2, offB);
;             PG8_BAR; PG8_WAIT_L(0); PG8_MMA(0, 1, At, B1); PG8_BAR;
;             PG8_LDA(At, 0, 1); PG8_STAGE(PG8_SA(0, 0), a2, offA);
;             PG8_BAR; PG8_WAIT_L(0); PG8_MMA(1, 0, At, B0); PG8_BAR; PG8_SCHED;
;             PG8_STAGE(PG8_SB(0, 1), b2 + hsB, offB);
;             PG8_WAIT_V(6); PG8_BAR; PG8_MMA(1, 1, At, B1); PG8_BAR;
	s_waitcnt lgkmcnt(0)
	s_setprio 1
	s_waitcnt lgkmcnt(0)
	v_mfma_f32_16x16x32_bf16 v[126:129], v[140:143], v[156:159], v[126:129]
	v_mfma_f32_16x16x32_bf16 v[122:125], v[148:151], v[156:159], v[122:125]
	v_mfma_f32_16x16x32_bf16 v[110:113], v[140:143], v[164:167], v[110:113]
	v_mfma_f32_16x16x32_bf16 v[106:109], v[148:151], v[164:167], v[106:109]
	v_mfma_f32_16x16x32_bf16 v[94:97], v[140:143], v[172:175], v[94:97]
	v_mfma_f32_16x16x32_bf16 v[90:93], v[148:151], v[172:175], v[90:93]
	v_mfma_f32_16x16x32_bf16 v[78:81], v[140:143], v[180:183], v[78:81]
	v_mfma_f32_16x16x32_bf16 v[74:77], v[148:151], v[180:183], v[74:77]
	v_mfma_f32_16x16x32_bf16 v[126:129], v[144:147], v[160:163], v[126:129]
	v_mfma_f32_16x16x32_bf16 v[122:125], v[152:155], v[160:163], v[122:125]
	v_mfma_f32_16x16x32_bf16 v[110:113], v[144:147], v[168:171], v[110:113]
	v_mfma_f32_16x16x32_bf16 v[106:109], v[152:155], v[168:171], v[106:109]
	v_mfma_f32_16x16x32_bf16 v[94:97], v[144:147], v[176:179], v[94:97]
	v_mfma_f32_16x16x32_bf16 v[90:93], v[152:155], v[176:179], v[90:93]
	v_mfma_f32_16x16x32_bf16 v[78:81], v[144:147], v[184:187], v[78:81]
	v_mfma_f32_16x16x32_bf16 v[74:77], v[152:155], v[184:187], v[74:77]
	s_setprio 0
	s_barrier
	s_add_i32 s65, 0, 0x14000
	v_add_u32_e32 v134, s65, v137
	ds_read_b128 v[188:191], v134
	ds_read_b128 v[192:195], v134 offset:1024
	ds_read_b128 v[196:199], v134 offset:2048
	ds_read_b128 v[200:203], v134 offset:3072
	v_lshl_add_u64 v[134:135], s[62:63], 0, v[0:1]
	s_add_i32 s62, s64, s29
	s_mov_b32 m0, s62
	v_lshl_add_u64 v[204:205], v[134:135], 0, s[56:57]
	global_load_lds_dwordx4 v[134:135], off
	s_add_i32 m0, s62, 0x2000
	s_nop 0
	global_load_lds_dwordx4 v[204:205], off
	s_barrier
	s_waitcnt lgkmcnt(0)
	s_setprio 1
	s_waitcnt lgkmcnt(0)
	v_mfma_f32_16x16x32_bf16 v[118:121], v[188:191], v[156:159], v[118:121]
	v_mfma_f32_16x16x32_bf16 v[114:117], v[196:199], v[156:159], v[114:117]
	v_mfma_f32_16x16x32_bf16 v[102:105], v[188:191], v[164:167], v[102:105]
	v_mfma_f32_16x16x32_bf16 v[98:101], v[196:199], v[164:167], v[98:101]
	v_mfma_f32_16x16x32_bf16 v[86:89], v[188:191], v[172:175], v[86:89]
	v_mfma_f32_16x16x32_bf16 v[82:85], v[196:199], v[172:175], v[82:85]
	v_mfma_f32_16x16x32_bf16 v[70:73], v[188:191], v[180:183], v[70:73]
	v_mfma_f32_16x16x32_bf16 v[66:69], v[196:199], v[180:183], v[66:69]
	v_mfma_f32_16x16x32_bf16 v[118:121], v[192:195], v[160:163], v[118:121]
	v_mfma_f32_16x16x32_bf16 v[114:117], v[200:203], v[160:163], v[114:117]
	v_mfma_f32_16x16x32_bf16 v[102:105], v[192:195], v[168:171], v[102:105]
	v_mfma_f32_16x16x32_bf16 v[98:101], v[200:203], v[168:171], v[98:101]
	v_mfma_f32_16x16x32_bf16 v[86:89], v[192:195], v[176:179], v[86:89]
	v_mfma_f32_16x16x32_bf16 v[82:85], v[200:203], v[176:179], v[82:85]
	v_mfma_f32_16x16x32_bf16 v[70:73], v[192:195], v[184:187], v[70:73]
	v_mfma_f32_16x16x32_bf16 v[66:69], v[200:203], v[184:187], v[66:69]
	s_setprio 0
	s_mov_b32 m0, s30
	v_lshl_add_u64 v[204:205], s[58:59], 0, v[130:131]
	s_barrier
	ds_read_b128 v[156:159], v138 offset:16384
	ds_read_b128 v[160:163], v138 offset:17408
	ds_read_b128 v[164:167], v138 offset:18432
	ds_read_b128 v[168:171], v138 offset:19456
	ds_read_b128 v[172:175], v138 offset:20480
	ds_read_b128 v[176:179], v138 offset:21504
	ds_read_b128 v[180:183], v138 offset:22528
	ds_read_b128 v[184:187], v138 offset:23552
	global_load_lds_dwordx4 v[204:205], off
	v_lshl_add_u64 v[206:207], v[204:205], 0, s[56:57]
	s_mov_b32 m0, s31
	s_nop 0
	global_load_lds_dwordx4 v[206:207], off
	s_barrier
	s_waitcnt lgkmcnt(0)
	s_setprio 1
	s_waitcnt lgkmcnt(0)
	v_mfma_f32_16x16x32_bf16 v[62:65], v[140:143], v[156:159], v[62:65]
	v_mfma_f32_16x16x32_bf16 v[58:61], v[148:151], v[156:159], v[58:61]
	v_mfma_f32_16x16x32_bf16 v[46:49], v[140:143], v[164:167], v[46:49]
	v_mfma_f32_16x16x32_bf16 v[42:45], v[148:151], v[164:167], v[42:45]
	v_mfma_f32_16x16x32_bf16 v[30:33], v[140:143], v[172:175], v[30:33]
	v_mfma_f32_16x16x32_bf16 v[26:29], v[148:151], v[172:175], v[26:29]
	v_mfma_f32_16x16x32_bf16 v[14:17], v[140:143], v[180:183], v[14:17]
	v_mfma_f32_16x16x32_bf16 v[10:13], v[148:151], v[180:183], v[10:13]
	v_mfma_f32_16x16x32_bf16 v[62:65], v[144:147], v[160:163], v[62:65]
	v_mfma_f32_16x16x32_bf16 v[58:61], v[152:155], v[160:163], v[58:61]
	v_mfma_f32_16x16x32_bf16 v[46:49], v[144:147], v[168:171], v[46:49]
	v_mfma_f32_16x16x32_bf16 v[42:45], v[152:155], v[168:171], v[42:45]
	v_mfma_f32_16x16x32_bf16 v[30:33], v[144:147], v[176:179], v[30:33]
	v_mfma_f32_16x16x32_bf16 v[26:29], v[152:155], v[176:179], v[26:29]
	v_mfma_f32_16x16x32_bf16 v[14:17], v[144:147], v[184:187], v[14:17]
	v_mfma_f32_16x16x32_bf16 v[10:13], v[152:155], v[184:187], v[10:13]
	s_setprio 0
	s_barrier
	s_add_i32 s58, s65, s29
	v_lshl_add_u64 v[140:141], v[134:135], 0, s[60:61]
	s_mov_b32 m0, s58
	s_nop 0
	global_load_lds_dwordx4 v[140:141], off
	v_lshl_add_u64 v[140:141], v[134:135], 0, s[74:75]
	s_add_i32 m0, s58, 0x2000
	s_nop 0
	global_load_lds_dwordx4 v[140:141], off
	s_waitcnt vmcnt(6)
	s_barrier
	s_setprio 1
	v_mfma_f32_16x16x32_bf16 v[54:57], v[188:191], v[156:159], v[54:57]
	v_mfma_f32_16x16x32_bf16 v[50:53], v[196:199], v[156:159], v[50:53]
	v_mfma_f32_16x16x32_bf16 v[38:41], v[188:191], v[164:167], v[38:41]
	v_mfma_f32_16x16x32_bf16 v[34:37], v[196:199], v[164:167], v[34:37]
	v_mfma_f32_16x16x32_bf16 v[22:25], v[188:191], v[172:175], v[22:25]
	v_mfma_f32_16x16x32_bf16 v[18:21], v[196:199], v[172:175], v[18:21]
	v_mfma_f32_16x16x32_bf16 v[6:9], v[188:191], v[180:183], v[6:9]
	v_mfma_f32_16x16x32_bf16 v[2:5], v[196:199], v[180:183], v[2:5]
	v_mfma_f32_16x16x32_bf16 v[54:57], v[192:195], v[160:163], v[54:57]
	v_mfma_f32_16x16x32_bf16 v[50:53], v[200:203], v[160:163], v[50:53]
	v_mfma_f32_16x16x32_bf16 v[38:41], v[192:195], v[168:171], v[38:41]
	v_mfma_f32_16x16x32_bf16 v[34:37], v[200:203], v[168:171], v[34:37]
	v_mfma_f32_16x16x32_bf16 v[22:25], v[192:195], v[176:179], v[22:25]
	v_mfma_f32_16x16x32_bf16 v[18:21], v[200:203], v[176:179], v[18:21]
	v_mfma_f32_16x16x32_bf16 v[6:9], v[192:195], v[184:187], v[6:9]
	v_mfma_f32_16x16x32_bf16 v[2:5], v[200:203], v[184:187], v[2:5]
	s_setprio 0
	s_add_i32 s58, 0, 0x18000
	v_add_u32_e32 v136, s58, v137
	s_barrier
; #define PG8_STAGE(bufoff, gbase, voff) do { _Pragma("unroll") for (int _i = 0; _i < 2; ++_i) \
;         __builtin_amdgcn_global_load_lds((const unsigned*)((const char*)(gbase) + (size_t)_i * vst##voff + v##voff), (LAS unsigned*)(lds + (bufoff) + ldsw + _i * 8192), 16, 0, 0); } while (0)
; #define PG8_LDA(dst, b, h) do { _Pragma("unroll") for (int m = 0; m < 4; ++m) _Pragma("unroll") for (int k = 0; k < 2; ++k) dst[m][k] = *(const LAS bf16x8*)(lds + PG8_SA(b, h) + aoff + m * 2048 + k * 1024); } while (0)
; #define PG8_LDB(dst, b, h) do { _Pragma("unroll") for (int n = 0; n < 2; ++n) _Pragma("unroll") for (int k = 0; k < 2; ++k) dst[n][k] = *(const LAS bf16x8*)(lds + PG8_SB(b, h) + boff + n * 2048 + k * 1024); } while (0)
; #define PG8_MMA(ai, bj, At, Bt) do { __builtin_amdgcn_s_setprio(1); _Pragma("unroll") for (int m = 0; m < 4; ++m) _Pragma("unroll") for (int n = 0; n < 2; ++n) _Pragma("unroll") for (int k = 0; k < 2; ++k) \
;         acc[ai][bj][m][n] = __builtin_amdgcn_mfma_f32_16x16x32_bf16(Bt[n][k], At[m][k], acc[ai][bj][m][n], 0, 0, 0); __builtin_amdgcn_s_setprio(0); } while (0)
; #define PG8_WAIT_V(n) asm volatile("s_waitcnt vmcnt(" #n ")" ::: "memory")
; #define PG8_WAIT_L(n) asm volatile("s_waitcnt lgkmcnt(" #n ")" ::: "memory")
; #define PG8_BAR __builtin_amdgcn_s_barrier()
; #define PG8_SCHED __builtin_amdgcn_sched_barrier(0)
; template <class Epi>
; DI void gemm_phase(LAS unsigned char* lds, const Gemm g, const StaticOrder& S, const Epi& E, const int tid) {
;     ...
;             PG8_LDB(B0, 1, 0); PG8_SCHED; PG8_LDA(At, 1, 0); PG8_STAGE(PG8_SA(0, 1), a2 + hsA, offA);
;             PG8_WAIT_L(8); PG8_BAR; PG8_WAIT_L(0); PG8_MMA(0, 0, At, B0); PG8_BAR; PG8_SCHED;
;             PG8_LDB(B1, 1, 1); PG8_STAGE(PG8_SB(1, 0), b3, offB);
;             PG8_BAR; PG8_WAIT_L(0); PG8_MMA(0, 1, At, B1); PG8_BAR;
;             PG8_LDA(At, 1, 1); PG8_STAGE(PG8_SA(1, 0), a3, offA);
;             PG8_BAR; PG8_WAIT_L(0); PG8_MMA(1, 0, At, B0); PG8_BAR; PG8_SCHED;
;             PG8_STAGE(PG8_SB(1, 1), b3 + hsB, offB);
;             PG8_WAIT_V(6); PG8_BAR; PG8_MMA(1, 1, At, B1); PG8_BAR;
	ds_read_b128 v[140:143], v136
	ds_read_b128 v[144:147], v136 offset:1024
	ds_read_b128 v[148:151], v136 offset:2048
	ds_read_b128 v[152:155], v136 offset:3072
	s_mov_b32 m0, s34
	v_lshl_add_u64 v[188:189], v[204:205], 0, s[60:61]
	ds_read_b128 v[156:159], v138 offset:32768
	ds_read_b128 v[160:163], v138 offset:33792
	ds_read_b128 v[164:167], v138 offset:34816
	ds_read_b128 v[168:171], v138 offset:35840
	ds_read_b128 v[172:175], v138 offset:36864
	ds_read_b128 v[176:179], v138 offset:37888
	ds_read_b128 v[180:183], v138 offset:38912
	ds_read_b128 v[184:187], v138 offset:39936
	global_load_lds_dwordx4 v[188:189], off
	v_lshl_add_u64 v[188:189], v[204:205], 0, s[74:75]
	s_mov_b32 m0, s35
	s_nop 0
	global_load_lds_dwordx4 v[188:189], off
	s_waitcnt lgkmcnt(8)
	s_barrier
	s_waitcnt lgkmcnt(0)
	s_setprio 1
	s_waitcnt lgkmcnt(0)
	v_mfma_f32_16x16x32_bf16 v[126:129], v[140:143], v[156:159], v[126:129]
	v_mfma_f32_16x16x32_bf16 v[122:125], v[148:151], v[156:159], v[122:125]
	v_mfma_f32_16x16x32_bf16 v[110:113], v[140:143], v[164:167], v[110:113]
	v_mfma_f32_16x16x32_bf16 v[106:109], v[148:151], v[164:167], v[106:109]
	v_mfma_f32_16x16x32_bf16 v[94:97], v[140:143], v[172:175], v[94:97]
	v_mfma_f32_16x16x32_bf16 v[90:93], v[148:151], v[172:175], v[90:93]
	v_mfma_f32_16x16x32_bf16 v[78:81], v[140:143], v[180:183], v[78:81]
	v_mfma_f32_16x16x32_bf16 v[74:77], v[148:151], v[180:183], v[74:77]
	v_mfma_f32_16x16x32_bf16 v[126:129], v[144:147], v[160:163], v[126:129]
	v_mfma_f32_16x16x32_bf16 v[122:125], v[152:155], v[160:163], v[122:125]
	v_mfma_f32_16x16x32_bf16 v[110:113], v[144:147], v[168:171], v[110:113]
	v_mfma_f32_16x16x32_bf16 v[106:109], v[152:155], v[168:171], v[106:109]
	v_mfma_f32_16x16x32_bf16 v[94:97], v[144:147], v[176:179], v[94:97]
	v_mfma_f32_16x16x32_bf16 v[90:93], v[152:155], v[176:179], v[90:93]
	v_mfma_f32_16x16x32_bf16 v[78:81], v[144:147], v[184:187], v[78:81]
	v_mfma_f32_16x16x32_bf16 v[74:77], v[152:155], v[184:187], v[74:77]
	s_setprio 0
	s_barrier
	s_add_i32 s59, 0, 0x1c000
	s_add_i32 s58, s58, s29
	v_add_u32_e32 v136, s59, v137
	v_lshl_add_u64 v[206:207], v[134:135], 0, s[88:89]
	s_mov_b32 m0, s58
	ds_read_b128 v[188:191], v136
	ds_read_b128 v[192:195], v136 offset:1024
	ds_read_b128 v[196:199], v136 offset:2048
	ds_read_b128 v[200:203], v136 offset:3072
	global_load_lds_dwordx4 v[206:207], off
	v_lshl_add_u64 v[206:207], v[134:135], 0, s[72:73]
	s_add_i32 m0, s58, 0x2000
	s_nop 0
	global_load_lds_dwordx4 v[206:207], off
	s_barrier
	s_waitcnt lgkmcnt(0)
	s_setprio 1
	s_waitcnt lgkmcnt(0)
	v_mfma_f32_16x16x32_bf16 v[118:121], v[188:191], v[156:159], v[118:121]
	v_mfma_f32_16x16x32_bf16 v[114:117], v[196:199], v[156:159], v[114:117]
	v_mfma_f32_16x16x32_bf16 v[102:105], v[188:191], v[164:167], v[102:105]
	v_mfma_f32_16x16x32_bf16 v[98:101], v[196:199], v[164:167], v[98:101]
	v_mfma_f32_16x16x32_bf16 v[86:89], v[188:191], v[172:175], v[86:89]
	v_mfma_f32_16x16x32_bf16 v[82:85], v[196:199], v[172:175], v[82:85]
	v_mfma_f32_16x16x32_bf16 v[70:73], v[188:191], v[180:183], v[70:73]
	v_mfma_f32_16x16x32_bf16 v[66:69], v[196:199], v[180:183], v[66:69]
	v_mfma_f32_16x16x32_bf16 v[118:121], v[192:195], v[160:163], v[118:121]
	v_mfma_f32_16x16x32_bf16 v[114:117], v[200:203], v[160:163], v[114:117]
	v_mfma_f32_16x16x32_bf16 v[102:105], v[192:195], v[168:171], v[102:105]
	v_mfma_f32_16x16x32_bf16 v[98:101], v[200:203], v[168:171], v[98:101]
	v_mfma_f32_16x16x32_bf16 v[86:89], v[192:195], v[176:179], v[86:89]
	v_mfma_f32_16x16x32_bf16 v[82:85], v[200:203], v[176:179], v[82:85]
	v_mfma_f32_16x16x32_bf16 v[70:73], v[192:195], v[184:187], v[70:73]
	v_mfma_f32_16x16x32_bf16 v[66:69], v[200:203], v[184:187], v[66:69]
	s_setprio 0
	s_mov_b32 m0, s38
	v_lshl_add_u64 v[206:207], v[204:205], 0, s[88:89]
	s_barrier
	ds_read_b128 v[156:159], v138 offset:49152
	ds_read_b128 v[160:163], v138 offset:50176
	ds_read_b128 v[164:167], v138 offset:51200
	ds_read_b128 v[168:171], v138 offset:52224
	ds_read_b128 v[172:175], v138 offset:53248
	ds_read_b128 v[176:179], v138 offset:54272
	ds_read_b128 v[180:183], v138 offset:55296
	ds_read_b128 v[184:187], v138 offset:56320
	global_load_lds_dwordx4 v[206:207], off
	v_lshl_add_u64 v[204:205], v[204:205], 0, s[72:73]
	s_mov_b32 m0, s39
	s_nop 0
	global_load_lds_dwordx4 v[204:205], off
	s_barrier
	s_waitcnt lgkmcnt(0)
	s_setprio 1
	s_waitcnt lgkmcnt(0)
	v_mfma_f32_16x16x32_bf16 v[62:65], v[140:143], v[156:159], v[62:65]
	v_mfma_f32_16x16x32_bf16 v[58:61], v[148:151], v[156:159], v[58:61]
	v_mfma_f32_16x16x32_bf16 v[46:49], v[140:143], v[164:167], v[46:49]
	v_mfma_f32_16x16x32_bf16 v[42:45], v[148:151], v[164:167], v[42:45]
	v_mfma_f32_16x16x32_bf16 v[30:33], v[140:143], v[172:175], v[30:33]
	v_mfma_f32_16x16x32_bf16 v[26:29], v[148:151], v[172:175], v[26:29]
	v_mfma_f32_16x16x32_bf16 v[14:17], v[140:143], v[180:183], v[14:17]
	v_mfma_f32_16x16x32_bf16 v[10:13], v[148:151], v[180:183], v[10:13]
	v_mfma_f32_16x16x32_bf16 v[62:65], v[144:147], v[160:163], v[62:65]
	v_mfma_f32_16x16x32_bf16 v[58:61], v[152:155], v[160:163], v[58:61]
	v_mfma_f32_16x16x32_bf16 v[46:49], v[144:147], v[168:171], v[46:49]
	v_mfma_f32_16x16x32_bf16 v[42:45], v[152:155], v[168:171], v[42:45]
	v_mfma_f32_16x16x32_bf16 v[30:33], v[144:147], v[176:179], v[30:33]
	v_mfma_f32_16x16x32_bf16 v[26:29], v[152:155], v[176:179], v[26:29]
	v_mfma_f32_16x16x32_bf16 v[14:17], v[144:147], v[184:187], v[14:17]
	v_mfma_f32_16x16x32_bf16 v[10:13], v[152:155], v[184:187], v[10:13]
	s_setprio 0
	s_barrier
	s_add_i32 s58, s59, s29
	v_lshl_add_u64 v[140:141], v[134:135], 0, s[48:49]
	s_mov_b32 m0, s58
	v_lshl_add_u64 v[134:135], v[134:135], 0, s[66:67]
	global_load_lds_dwordx4 v[140:141], off
	s_add_i32 m0, s58, 0x2000
	s_nop 0
	global_load_lds_dwordx4 v[134:135], off
	s_waitcnt vmcnt(6)
	s_barrier
; DI unsigned pk2(float lo, float hi) { fv2 v = {lo, hi}; return __builtin_bit_cast(unsigned, __builtin_convertvector(v, bfv2)); }
; DI float sigm(float x) { return rcpf(1.0f + ex2(-x * LOG2E)); }
; DI int lane_id() { int l; asm volatile("v_mbcnt_lo_u32_b32 %0, -1, 0\n\tv_mbcnt_hi_u32_b32 %0, -1, %0" : "=v"(l)); return l; }
; #define PG8_MMA(ai, bj, At, Bt) do { __builtin_amdgcn_s_setprio(1); _Pragma("unroll") for (int m = 0; m < 4; ++m) _Pragma("unroll") for (int n = 0; n < 2; ++n) _Pragma("unroll") for (int k = 0; k < 2; ++k) \
;         acc[ai][bj][m][n] = __builtin_amdgcn_mfma_f32_16x16x32_bf16(Bt[n][k], At[m][k], acc[ai][bj][m][n], 0, 0, 0); __builtin_amdgcn_s_setprio(0); } while (0)
; #define PG8_WAIT_V(n) asm volatile("s_waitcnt vmcnt(" #n ")" ::: "memory")
; #define PG8_BAR __builtin_amdgcn_s_barrier()
; template <class Epi>
; DI void gemm_phase(LAS unsigned char* lds, const Gemm g, const StaticOrder& S, const Epi& E, const int tid) {
;     ...
;             PG8_WAIT_V(6); PG8_BAR; PG8_MMA(1, 1, At, B1); PG8_BAR;
;         }
;         if constexpr (!Epi::AFTER_DRAIN) { const int t2 = lane_id(); E(acc, cur, wr, wc, t2 & 15, t2 >> 4); }
;         if (!has_next) break;
;     DI void operator()(const AccT& acc, const Unit& u, int wr, int wc, int fr, int fq) const {
;     ...
;         for (int ai = 0; ai < 2; ++ai)
; #pragma unroll
;             for (int m = 0; m < 4; ++m) {
;                 const int row = u.pm * 256 + ai * 128 + wr * 64 + m * 16 + fr;
;                 const float rs = rsqrtf(sv_[ai][m] * (1.0f / 1024.0f) + EPS);
; #pragma unroll
;                 for (int bj = 0; bj < 2; ++bj) {
;                     const int col0 = u.pn * 256 + bj * 128 + wc * 32 + fq * 8;
;                     const f32x4 g = acc[ai][bj][m][0] * rs, uu = acc[ai][bj][m][1] * rs; f32x4 r;
; #pragma unroll
;                     for (int j = 0; j < 4; ++j) r[j] = g[j] * sigm(g[j]) * uu[j];
;                     u32x2 w; w.x = pk2(r[0], r[1]); w.y = pk2(r[2], r[3]); *(u32x2*)(ACT + (size_t)row * DFF + (col0 >> 1)) = w;
	s_setprio 1
	v_mfma_f32_16x16x32_bf16 v[54:57], v[188:191], v[156:159], v[54:57]
	v_mfma_f32_16x16x32_bf16 v[50:53], v[196:199], v[156:159], v[50:53]
	v_mfma_f32_16x16x32_bf16 v[38:41], v[188:191], v[164:167], v[38:41]
	v_mfma_f32_16x16x32_bf16 v[34:37], v[196:199], v[164:167], v[34:37]
	v_mfma_f32_16x16x32_bf16 v[22:25], v[188:191], v[172:175], v[22:25]
	v_mfma_f32_16x16x32_bf16 v[18:21], v[196:199], v[172:175], v[18:21]
	v_mfma_f32_16x16x32_bf16 v[6:9], v[188:191], v[180:183], v[6:9]
	v_mfma_f32_16x16x32_bf16 v[2:5], v[196:199], v[180:183], v[2:5]
	v_mfma_f32_16x16x32_bf16 v[54:57], v[192:195], v[160:163], v[54:57]
	v_mfma_f32_16x16x32_bf16 v[50:53], v[200:203], v[160:163], v[50:53]
	v_mfma_f32_16x16x32_bf16 v[38:41], v[192:195], v[168:171], v[38:41]
	v_mfma_f32_16x16x32_bf16 v[34:37], v[200:203], v[168:171], v[34:37]
	v_mfma_f32_16x16x32_bf16 v[22:25], v[192:195], v[176:179], v[22:25]
	v_mfma_f32_16x16x32_bf16 v[18:21], v[200:203], v[176:179], v[18:21]
	v_mfma_f32_16x16x32_bf16 v[6:9], v[192:195], v[184:187], v[6:9]
	v_mfma_f32_16x16x32_bf16 v[2:5], v[200:203], v[184:187], v[2:5]
	s_setprio 0
	s_add_i32 s47, s47, 2
	s_add_u32 s22, s22, 0x100
	s_addc_u32 s23, s23, 0
	s_add_u32 s24, s24, 0x100
	s_addc_u32 s25, s25, 0
	s_cmp_gt_u32 s47, 13
	s_barrier
	s_cbranch_scc0 .LBB0_1786
	s_lshl_b32 s11, s42, 8
	s_add_i32 s11, s11, s36
	v_mbcnt_lo_u32_b32 v136, -1, 0
	v_mbcnt_hi_u32_b32 v136, -1, v136
	s_mov_b32 s65, 0x800000
	v_and_or_b32 v134, v136, 15, s11
	v_ashrrev_i32_e32 v135, 31, v134
	v_lshl_add_u64 v[152:153], v[134:135], 2, s[8:9]
	s_waitcnt vmcnt(6)
	v_mov_b32_e32 v154, v242
	v_mov_b32_e32 v151, v243
	v_mov_b32_e32 v149, v244
	v_mov_b32_e32 v147, v245
	v_mov_b32_e32 v145, v246
	v_mov_b32_e32 v143, v247
	v_mov_b32_e32 v141, v248
	v_mov_b32_e32 v139, v249
	s_lshl_b32 s11, s41, 8
	v_ashrrev_i32_e32 v136, 1, v136
	v_and_b32_e32 v136, -8, v136
	s_or_b32 s11, s11, s37
	v_add_u32_e32 v155, s11, v136
	s_movk_i32 s11, 0x1600
	v_or_b32_e32 v150, 16, v134
	v_or_b32_e32 v148, 32, v134
	v_or_b32_e32 v146, 48, v134
	v_add_u32_e32 v144, 0x80, v134
	v_add_u32_e32 v142, 0x90, v134
	v_add_u32_e32 v140, 0xa0, v134
	v_add_u32_e32 v135, 0xb0, v134
	s_mov_b32 s41, s10
	s_mov_b32 s42, s14
	s_mov_b64 s[24:25], s[18:19]
	s_waitcnt vmcnt(6)
	v_fmamk_f32 v136, v154, 0x3a800000, v225
	v_cmp_gt_f32_e32 vcc, s65, v136
	v_mul_f32_e32 v152, 0x4b800000, v136
	s_nop 0
	v_cndmask_b32_e32 v136, v136, v152, vcc
	v_rsq_f32_e32 v136, v136
	s_nop 0
	v_mul_f32_e32 v152, 0x45800000, v136
	v_cndmask_b32_e32 v136, v136, v152, vcc
	v_pk_mul_f32 v[126:127], v[126:127], v[136:137] op_sel_hi:[1,0]
	v_pk_mul_f32 v[122:123], v[122:123], v[136:137] op_sel_hi:[1,0]
	v_mul_f32_e32 v152, 0xbfb8aa3b, v126
	v_mul_f32_e32 v153, 0xbfb8aa3b, v127
	v_exp_f32_e32 v152, v152
	v_exp_f32_e32 v153, v153
	v_pk_mul_f32 v[124:125], v[124:125], v[136:137] op_sel_hi:[1,0]
	v_pk_mul_f32 v[118:119], v[118:119], v[136:137] op_sel_hi:[1,0]
	v_add_f32_e32 v152, 1.0, v152
	v_add_f32_e32 v153, 1.0, v153
	v_rcp_f32_e32 v152, v152
	v_rcp_f32_e32 v153, v153
	v_pk_mul_f32 v[114:115], v[114:115], v[136:137] op_sel_hi:[1,0]
	v_pk_mul_f32 v[116:117], v[116:117], v[136:137] op_sel_hi:[1,0]
	v_pk_mul_f32 v[126:127], v[126:127], v[152:153]
	s_nop 0
	v_pk_mul_f32 v[122:123], v[122:123], v[126:127]
	v_pk_mul_f32 v[126:127], v[128:129], v[136:137] op_sel_hi:[1,0]
	s_nop 0
	v_mul_f32_e32 v128, 0xbfb8aa3b, v126
	v_mul_f32_e32 v129, 0xbfb8aa3b, v127
	v_exp_f32_e32 v128, v128
	v_exp_f32_e32 v129, v129
	v_add_f32_e32 v128, 1.0, v128
	v_add_f32_e32 v129, 1.0, v129
	v_rcp_f32_e32 v128, v128
	v_rcp_f32_e32 v129, v129
	s_nop 0
	v_pk_mul_f32 v[126:127], v[126:127], v[128:129]
	s_nop 0
	v_pk_mul_f32 v[124:125], v[124:125], v[126:127]
	v_cvt_pk_bf16_f32 v126, v122, v123
	v_cvt_pk_bf16_f32 v127, v124, v125
	v_ashrrev_i32_e32 v124, 1, v155
	v_mov_b64_e32 v[122:123], s[6:7]
	v_ashrrev_i32_e32 v125, 31, v124
	v_mad_i64_i32 v[128:129], s[22:23], v134, s11, v[122:123]
	v_lshlrev_b64 v[124:125], 1, v[124:125]
	v_lshl_add_u64 v[152:153], v[128:129], 0, v[124:125]
	global_store_dwordx2 v[152:153], v[126:127], off
	v_mul_f32_e32 v126, 0xbfb8aa3b, v118
	v_mul_f32_e32 v127, 0xbfb8aa3b, v119
	v_exp_f32_e32 v126, v126
	v_exp_f32_e32 v127, v127
	v_add_f32_e32 v126, 1.0, v126
	v_add_f32_e32 v127, 1.0, v127
	v_rcp_f32_e32 v126, v126
	v_rcp_f32_e32 v127, v127
	s_nop 0
	v_pk_mul_f32 v[118:119], v[118:119], v[126:127]
	s_nop 0
	v_pk_mul_f32 v[114:115], v[114:115], v[118:119]
	v_pk_mul_f32 v[118:119], v[120:121], v[136:137] op_sel_hi:[1,0]
	s_nop 0
	v_mul_f32_e32 v120, 0xbfb8aa3b, v118
	v_mul_f32_e32 v121, 0xbfb8aa3b, v119
	v_exp_f32_e32 v120, v120
	v_exp_f32_e32 v121, v121
	v_add_f32_e32 v120, 1.0, v120
	v_add_f32_e32 v121, 1.0, v121
	v_rcp_f32_e32 v120, v120
	v_rcp_f32_e32 v121, v121
	s_nop 0
	v_pk_mul_f32 v[118:119], v[118:119], v[120:121]
	v_add_u32_e32 v120, 0x80, v155
	v_pk_mul_f32 v[116:117], v[116:117], v[118:119]
	v_cvt_pk_bf16_f32 v118, v114, v115
	v_ashrrev_i32_e32 v114, 1, v120
	v_ashrrev_i32_e32 v115, 31, v114
	v_lshlrev_b64 v[114:115], 1, v[114:115]
	v_cvt_pk_bf16_f32 v119, v116, v117
	v_lshl_add_u64 v[116:117], v[128:129], 0, v[114:115]
	global_store_dwordx2 v[116:117], v[118:119], off
	v_fmamk_f32 v116, v151, 0x3a800000, v225
	v_cmp_gt_f32_e32 vcc, s65, v116
	v_mul_f32_e32 v117, 0x4b800000, v116
	s_nop 0
	v_cndmask_b32_e32 v116, v116, v117, vcc
	v_rsq_f32_e32 v116, v116
	s_nop 0
	v_mul_f32_e32 v117, 0x45800000, v116
	v_cndmask_b32_e32 v116, v116, v117, vcc
	v_pk_mul_f32 v[110:111], v[110:111], v[116:117] op_sel_hi:[1,0]
	s_nop 0
	v_mul_f32_e32 v117, 0xbfb8aa3b, v110
	v_exp_f32_e32 v117, v117
	s_nop 0
	v_add_f32_e32 v117, 1.0, v117
; DI unsigned pk2(float lo, float hi) { fv2 v = {lo, hi}; return __builtin_bit_cast(unsigned, __builtin_convertvector(v, bfv2)); }
; DI float sigm(float x) { return rcpf(1.0f + ex2(-x * LOG2E)); }
;     DI void operator()(const AccT& acc, const Unit& u, int wr, int wc, int fr, int fq) const {
;     ...
;         for (int ai = 0; ai < 2; ++ai)
; #pragma unroll
;             for (int m = 0; m < 4; ++m) {
;                 const int row = u.pm * 256 + ai * 128 + wr * 64 + m * 16 + fr;
;                 const float rs = rsqrtf(sv_[ai][m] * (1.0f / 1024.0f) + EPS);
; #pragma unroll
;                 for (int bj = 0; bj < 2; ++bj) {
;                     const int col0 = u.pn * 256 + bj * 128 + wc * 32 + fq * 8;
;                     const f32x4 g = acc[ai][bj][m][0] * rs, uu = acc[ai][bj][m][1] * rs; f32x4 r;
; #pragma unroll
;                     for (int j = 0; j < 4; ++j) r[j] = g[j] * sigm(g[j]) * uu[j];
;                     u32x2 w; w.x = pk2(r[0], r[1]); w.y = pk2(r[2], r[3]); *(u32x2*)(ACT + (size_t)row * DFF + (col0 >> 1)) = w;
	v_rcp_f32_e32 v118, v117
	v_mul_f32_e32 v117, 0xbfb8aa3b, v111
	v_exp_f32_e32 v117, v117
	s_nop 0
	v_add_f32_e32 v117, 1.0, v117
	v_rcp_f32_e32 v119, v117
	v_pk_mul_f32 v[106:107], v[106:107], v[116:117] op_sel_hi:[1,0]
	v_pk_mul_f32 v[108:109], v[108:109], v[116:117] op_sel_hi:[1,0]
	v_pk_mul_f32 v[102:103], v[102:103], v[116:117] op_sel_hi:[1,0]
	v_pk_mul_f32 v[110:111], v[110:111], v[118:119]
	v_pk_mul_f32 v[98:99], v[98:99], v[116:117] op_sel_hi:[1,0]
	v_pk_mul_f32 v[106:107], v[106:107], v[110:111]
	v_pk_mul_f32 v[110:111], v[112:113], v[116:117] op_sel_hi:[1,0]
	v_cvt_pk_bf16_f32 v106, v106, v107
	v_mul_f32_e32 v112, 0xbfb8aa3b, v110
	v_mul_f32_e32 v113, 0xbfb8aa3b, v111
	v_exp_f32_e32 v112, v112
	v_exp_f32_e32 v113, v113
	v_pk_mul_f32 v[100:101], v[100:101], v[116:117] op_sel_hi:[1,0]
	v_add_f32_e32 v112, 1.0, v112
	v_add_f32_e32 v113, 1.0, v113
	v_rcp_f32_e32 v112, v112
	v_rcp_f32_e32 v113, v113
	s_nop 0
	v_pk_mul_f32 v[110:111], v[110:111], v[112:113]
	s_nop 0
	v_pk_mul_f32 v[108:109], v[108:109], v[110:111]
	s_nop 0
	v_cvt_pk_bf16_f32 v107, v108, v109
	v_mad_i64_i32 v[108:109], s[22:23], v150, s11, v[122:123]
	v_lshl_add_u64 v[110:111], v[108:109], 0, v[124:125]
	global_store_dwordx2 v[110:111], v[106:107], off
	v_mul_f32_e32 v106, 0xbfb8aa3b, v102
	v_mul_f32_e32 v107, 0xbfb8aa3b, v103
	v_exp_f32_e32 v106, v106
	v_exp_f32_e32 v107, v107
	v_add_f32_e32 v106, 1.0, v106
	v_add_f32_e32 v107, 1.0, v107
	v_rcp_f32_e32 v106, v106
	v_rcp_f32_e32 v107, v107
	s_nop 0
	v_pk_mul_f32 v[102:103], v[102:103], v[106:107]
	s_nop 0
	v_pk_mul_f32 v[98:99], v[98:99], v[102:103]
	v_pk_mul_f32 v[102:103], v[104:105], v[116:117] op_sel_hi:[1,0]
	v_cvt_pk_bf16_f32 v98, v98, v99
	v_mul_f32_e32 v104, 0xbfb8aa3b, v102
	v_mul_f32_e32 v105, 0xbfb8aa3b, v103
	v_exp_f32_e32 v104, v104
	v_exp_f32_e32 v105, v105
	v_add_f32_e32 v104, 1.0, v104
	v_add_f32_e32 v105, 1.0, v105
	v_rcp_f32_e32 v104, v104
	v_rcp_f32_e32 v105, v105
	s_nop 0
	v_pk_mul_f32 v[102:103], v[102:103], v[104:105]
	s_nop 0
	v_pk_mul_f32 v[100:101], v[100:101], v[102:103]
	s_nop 0
	v_cvt_pk_bf16_f32 v99, v100, v101
	v_lshl_add_u64 v[100:101], v[108:109], 0, v[114:115]
	global_store_dwordx2 v[100:101], v[98:99], off
	v_fmamk_f32 v98, v149, 0x3a800000, v225
	v_cmp_gt_f32_e32 vcc, s65, v98
	v_mul_f32_e32 v99, 0x4b800000, v98
	s_nop 0
	v_cndmask_b32_e32 v98, v98, v99, vcc
	v_rsq_f32_e32 v98, v98
	s_nop 0
	v_mul_f32_e32 v99, 0x45800000, v98
	v_cndmask_b32_e32 v98, v98, v99, vcc
	v_pk_mul_f32 v[94:95], v[94:95], v[98:99] op_sel_hi:[1,0]
	s_nop 0
	v_mul_f32_e32 v99, 0xbfb8aa3b, v94
	v_exp_f32_e32 v99, v99
	s_nop 0
	v_add_f32_e32 v99, 1.0, v99
	v_rcp_f32_e32 v100, v99
	v_mul_f32_e32 v99, 0xbfb8aa3b, v95
	v_exp_f32_e32 v99, v99
	s_nop 0
	v_add_f32_e32 v99, 1.0, v99
	v_rcp_f32_e32 v101, v99
	v_pk_mul_f32 v[90:91], v[90:91], v[98:99] op_sel_hi:[1,0]
	v_pk_mul_f32 v[92:93], v[92:93], v[98:99] op_sel_hi:[1,0]
	v_pk_mul_f32 v[86:87], v[86:87], v[98:99] op_sel_hi:[1,0]
	v_pk_mul_f32 v[94:95], v[94:95], v[100:101]
	v_pk_mul_f32 v[82:83], v[82:83], v[98:99] op_sel_hi:[1,0]
	v_pk_mul_f32 v[90:91], v[90:91], v[94:95]
	v_pk_mul_f32 v[94:95], v[96:97], v[98:99] op_sel_hi:[1,0]
	v_cvt_pk_bf16_f32 v90, v90, v91
	v_mul_f32_e32 v96, 0xbfb8aa3b, v94
	v_mul_f32_e32 v97, 0xbfb8aa3b, v95
	v_exp_f32_e32 v96, v96
	v_exp_f32_e32 v97, v97
	v_pk_mul_f32 v[84:85], v[84:85], v[98:99] op_sel_hi:[1,0]
	v_add_f32_e32 v96, 1.0, v96
	v_add_f32_e32 v97, 1.0, v97
	v_rcp_f32_e32 v96, v96
	v_rcp_f32_e32 v97, v97
	s_nop 0
	v_pk_mul_f32 v[94:95], v[94:95], v[96:97]
	s_nop 0
	v_pk_mul_f32 v[92:93], v[92:93], v[94:95]
	s_nop 0
	v_cvt_pk_bf16_f32 v91, v92, v93
	v_mad_i64_i32 v[92:93], s[22:23], v148, s11, v[122:123]
	v_lshl_add_u64 v[94:95], v[92:93], 0, v[124:125]
	global_store_dwordx2 v[94:95], v[90:91], off
	v_mul_f32_e32 v90, 0xbfb8aa3b, v86
	v_mul_f32_e32 v91, 0xbfb8aa3b, v87
	v_exp_f32_e32 v90, v90
	v_exp_f32_e32 v91, v91
	v_add_f32_e32 v90, 1.0, v90
	v_add_f32_e32 v91, 1.0, v91
	v_rcp_f32_e32 v90, v90
	v_rcp_f32_e32 v91, v91
	s_nop 0
	v_pk_mul_f32 v[86:87], v[86:87], v[90:91]
	s_nop 0
	v_pk_mul_f32 v[82:83], v[82:83], v[86:87]
	v_pk_mul_f32 v[86:87], v[88:89], v[98:99] op_sel_hi:[1,0]
	v_cvt_pk_bf16_f32 v82, v82, v83
	v_mul_f32_e32 v88, 0xbfb8aa3b, v86
	v_mul_f32_e32 v89, 0xbfb8aa3b, v87
	v_exp_f32_e32 v88, v88
	v_exp_f32_e32 v89, v89
	v_add_f32_e32 v88, 1.0, v88
	v_add_f32_e32 v89, 1.0, v89
	v_rcp_f32_e32 v88, v88
	v_rcp_f32_e32 v89, v89
	s_nop 0
	v_pk_mul_f32 v[86:87], v[86:87], v[88:89]
	s_nop 0
	v_pk_mul_f32 v[84:85], v[84:85], v[86:87]
	s_nop 0
	v_cvt_pk_bf16_f32 v83, v84, v85
	v_lshl_add_u64 v[84:85], v[92:93], 0, v[114:115]
	global_store_dwordx2 v[84:85], v[82:83], off
	v_fmamk_f32 v82, v147, 0x3a800000, v225
	v_cmp_gt_f32_e32 vcc, s65, v82
	v_mul_f32_e32 v83, 0x4b800000, v82
	s_nop 0
	v_cndmask_b32_e32 v82, v82, v83, vcc
	v_rsq_f32_e32 v82, v82
	s_nop 0
	v_mul_f32_e32 v83, 0x45800000, v82
	v_cndmask_b32_e32 v82, v82, v83, vcc
	v_pk_mul_f32 v[78:79], v[78:79], v[82:83] op_sel_hi:[1,0]
	s_nop 0
	v_mul_f32_e32 v83, 0xbfb8aa3b, v78
	v_exp_f32_e32 v83, v83
	s_nop 0
	v_add_f32_e32 v83, 1.0, v83
	v_rcp_f32_e32 v84, v83
	v_mul_f32_e32 v83, 0xbfb8aa3b, v79
	v_exp_f32_e32 v83, v83
	s_nop 0
	v_add_f32_e32 v83, 1.0, v83
	v_rcp_f32_e32 v85, v83
	v_pk_mul_f32 v[74:75], v[74:75], v[82:83] op_sel_hi:[1,0]
	v_pk_mul_f32 v[76:77], v[76:77], v[82:83] op_sel_hi:[1,0]
	v_pk_mul_f32 v[70:71], v[70:71], v[82:83] op_sel_hi:[1,0]
	v_pk_mul_f32 v[78:79], v[78:79], v[84:85]
	v_pk_mul_f32 v[66:67], v[66:67], v[82:83] op_sel_hi:[1,0]
	v_pk_mul_f32 v[74:75], v[74:75], v[78:79]
	v_pk_mul_f32 v[78:79], v[80:81], v[82:83] op_sel_hi:[1,0]
	v_cvt_pk_bf16_f32 v74, v74, v75
; DI unsigned pk2(float lo, float hi) { fv2 v = {lo, hi}; return __builtin_bit_cast(unsigned, __builtin_convertvector(v, bfv2)); }
; DI float sigm(float x) { return rcpf(1.0f + ex2(-x * LOG2E)); }
;     DI void operator()(const AccT& acc, const Unit& u, int wr, int wc, int fr, int fq) const {
;     ...
;         for (int ai = 0; ai < 2; ++ai)
; #pragma unroll
;             for (int m = 0; m < 4; ++m) {
;                 const int row = u.pm * 256 + ai * 128 + wr * 64 + m * 16 + fr;
;                 const float rs = rsqrtf(sv_[ai][m] * (1.0f / 1024.0f) + EPS);
; #pragma unroll
;                 for (int bj = 0; bj < 2; ++bj) {
;                     const int col0 = u.pn * 256 + bj * 128 + wc * 32 + fq * 8;
;                     const f32x4 g = acc[ai][bj][m][0] * rs, uu = acc[ai][bj][m][1] * rs; f32x4 r;
; #pragma unroll
;                     for (int j = 0; j < 4; ++j) r[j] = g[j] * sigm(g[j]) * uu[j];
;                     u32x2 w; w.x = pk2(r[0], r[1]); w.y = pk2(r[2], r[3]); *(u32x2*)(ACT + (size_t)row * DFF + (col0 >> 1)) = w;
	v_mul_f32_e32 v80, 0xbfb8aa3b, v78
	v_mul_f32_e32 v81, 0xbfb8aa3b, v79
	v_exp_f32_e32 v80, v80
	v_exp_f32_e32 v81, v81
	v_pk_mul_f32 v[68:69], v[68:69], v[82:83] op_sel_hi:[1,0]
	v_add_f32_e32 v80, 1.0, v80
	v_add_f32_e32 v81, 1.0, v81
	v_rcp_f32_e32 v80, v80
	v_rcp_f32_e32 v81, v81
	s_nop 0
	v_pk_mul_f32 v[78:79], v[78:79], v[80:81]
	s_nop 0
	v_pk_mul_f32 v[76:77], v[76:77], v[78:79]
	s_nop 0
	v_cvt_pk_bf16_f32 v75, v76, v77
	v_mad_i64_i32 v[76:77], s[22:23], v146, s11, v[122:123]
	v_lshl_add_u64 v[78:79], v[76:77], 0, v[124:125]
	global_store_dwordx2 v[78:79], v[74:75], off
	v_mul_f32_e32 v74, 0xbfb8aa3b, v70
	v_mul_f32_e32 v75, 0xbfb8aa3b, v71
	v_exp_f32_e32 v74, v74
	v_exp_f32_e32 v75, v75
	v_add_f32_e32 v74, 1.0, v74
	v_add_f32_e32 v75, 1.0, v75
	v_rcp_f32_e32 v74, v74
	v_rcp_f32_e32 v75, v75
	s_nop 0
	v_pk_mul_f32 v[70:71], v[70:71], v[74:75]
	s_nop 0
	v_pk_mul_f32 v[66:67], v[66:67], v[70:71]
	v_pk_mul_f32 v[70:71], v[72:73], v[82:83] op_sel_hi:[1,0]
	v_cvt_pk_bf16_f32 v66, v66, v67
	v_mul_f32_e32 v72, 0xbfb8aa3b, v70
	v_mul_f32_e32 v73, 0xbfb8aa3b, v71
	v_exp_f32_e32 v72, v72
	v_exp_f32_e32 v73, v73
	v_add_f32_e32 v72, 1.0, v72
	v_add_f32_e32 v73, 1.0, v73
	v_rcp_f32_e32 v72, v72
	v_rcp_f32_e32 v73, v73
	s_nop 0
	v_pk_mul_f32 v[70:71], v[70:71], v[72:73]
	s_nop 0
	v_pk_mul_f32 v[68:69], v[68:69], v[70:71]
	s_nop 0
	v_cvt_pk_bf16_f32 v67, v68, v69
	v_lshl_add_u64 v[68:69], v[76:77], 0, v[114:115]
	global_store_dwordx2 v[68:69], v[66:67], off
	v_fmamk_f32 v66, v145, 0x3a800000, v225
	v_cmp_gt_f32_e32 vcc, s65, v66
	v_mul_f32_e32 v67, 0x4b800000, v66
	s_nop 0
	v_cndmask_b32_e32 v66, v66, v67, vcc
	v_rsq_f32_e32 v66, v66
	s_nop 0
	v_mul_f32_e32 v67, 0x45800000, v66
	v_cndmask_b32_e32 v66, v66, v67, vcc
	v_pk_mul_f32 v[62:63], v[62:63], v[66:67] op_sel_hi:[1,0]
	s_nop 0
	v_mul_f32_e32 v67, 0xbfb8aa3b, v62
	v_exp_f32_e32 v67, v67
	s_nop 0
	v_add_f32_e32 v67, 1.0, v67
	v_rcp_f32_e32 v68, v67
	v_mul_f32_e32 v67, 0xbfb8aa3b, v63
	v_exp_f32_e32 v67, v67
	s_nop 0
	v_add_f32_e32 v67, 1.0, v67
	v_rcp_f32_e32 v69, v67
	v_pk_mul_f32 v[58:59], v[58:59], v[66:67] op_sel_hi:[1,0]
	v_pk_mul_f32 v[60:61], v[60:61], v[66:67] op_sel_hi:[1,0]
	v_pk_mul_f32 v[54:55], v[54:55], v[66:67] op_sel_hi:[1,0]
	v_pk_mul_f32 v[62:63], v[62:63], v[68:69]
	v_pk_mul_f32 v[50:51], v[50:51], v[66:67] op_sel_hi:[1,0]
	v_pk_mul_f32 v[58:59], v[58:59], v[62:63]
	v_pk_mul_f32 v[62:63], v[64:65], v[66:67] op_sel_hi:[1,0]
	v_cvt_pk_bf16_f32 v58, v58, v59
	v_mul_f32_e32 v64, 0xbfb8aa3b, v62
	v_mul_f32_e32 v65, 0xbfb8aa3b, v63
	v_exp_f32_e32 v64, v64
	v_exp_f32_e32 v65, v65
	v_pk_mul_f32 v[52:53], v[52:53], v[66:67] op_sel_hi:[1,0]
	v_add_f32_e32 v64, 1.0, v64
	v_add_f32_e32 v65, 1.0, v65
	v_rcp_f32_e32 v64, v64
	v_rcp_f32_e32 v65, v65
	s_nop 0
	v_pk_mul_f32 v[62:63], v[62:63], v[64:65]
	s_nop 0
	v_pk_mul_f32 v[60:61], v[60:61], v[62:63]
	s_nop 0
	v_cvt_pk_bf16_f32 v59, v60, v61
	v_mad_i64_i32 v[60:61], s[22:23], v144, s11, v[122:123]
	v_lshl_add_u64 v[62:63], v[60:61], 0, v[124:125]
	global_store_dwordx2 v[62:63], v[58:59], off
	v_mul_f32_e32 v58, 0xbfb8aa3b, v54
	v_mul_f32_e32 v59, 0xbfb8aa3b, v55
	v_exp_f32_e32 v58, v58
	v_exp_f32_e32 v59, v59
	v_add_f32_e32 v58, 1.0, v58
	v_add_f32_e32 v59, 1.0, v59
	v_rcp_f32_e32 v58, v58
	v_rcp_f32_e32 v59, v59
	s_nop 0
	v_pk_mul_f32 v[54:55], v[54:55], v[58:59]
	s_nop 0
	v_pk_mul_f32 v[50:51], v[50:51], v[54:55]
	v_pk_mul_f32 v[54:55], v[56:57], v[66:67] op_sel_hi:[1,0]
	v_cvt_pk_bf16_f32 v50, v50, v51
	v_mul_f32_e32 v56, 0xbfb8aa3b, v54
	v_mul_f32_e32 v57, 0xbfb8aa3b, v55
	v_exp_f32_e32 v56, v56
	v_exp_f32_e32 v57, v57
	v_add_f32_e32 v56, 1.0, v56
	v_add_f32_e32 v57, 1.0, v57
	v_rcp_f32_e32 v56, v56
	v_rcp_f32_e32 v57, v57
	s_nop 0
	v_pk_mul_f32 v[54:55], v[54:55], v[56:57]
	s_nop 0
	v_pk_mul_f32 v[52:53], v[52:53], v[54:55]
	s_nop 0
	v_cvt_pk_bf16_f32 v51, v52, v53
	v_lshl_add_u64 v[52:53], v[60:61], 0, v[114:115]
	global_store_dwordx2 v[52:53], v[50:51], off
	v_fmamk_f32 v50, v143, 0x3a800000, v225
	v_cmp_gt_f32_e32 vcc, s65, v50
	v_mul_f32_e32 v51, 0x4b800000, v50
	s_nop 0
	v_cndmask_b32_e32 v50, v50, v51, vcc
	v_rsq_f32_e32 v50, v50
	s_nop 0
	v_mul_f32_e32 v51, 0x45800000, v50
	v_cndmask_b32_e32 v50, v50, v51, vcc
	v_pk_mul_f32 v[46:47], v[46:47], v[50:51] op_sel_hi:[1,0]
	s_nop 0
	v_mul_f32_e32 v51, 0xbfb8aa3b, v46
	v_exp_f32_e32 v51, v51
	s_nop 0
	v_add_f32_e32 v51, 1.0, v51
	v_rcp_f32_e32 v52, v51
	v_mul_f32_e32 v51, 0xbfb8aa3b, v47
	v_exp_f32_e32 v51, v51
	s_nop 0
	v_add_f32_e32 v51, 1.0, v51
	v_rcp_f32_e32 v53, v51
	v_pk_mul_f32 v[42:43], v[42:43], v[50:51] op_sel_hi:[1,0]
	v_pk_mul_f32 v[44:45], v[44:45], v[50:51] op_sel_hi:[1,0]
	v_pk_mul_f32 v[38:39], v[38:39], v[50:51] op_sel_hi:[1,0]
	v_pk_mul_f32 v[46:47], v[46:47], v[52:53]
	v_pk_mul_f32 v[34:35], v[34:35], v[50:51] op_sel_hi:[1,0]
	v_pk_mul_f32 v[42:43], v[42:43], v[46:47]
	v_pk_mul_f32 v[46:47], v[48:49], v[50:51] op_sel_hi:[1,0]
	v_cvt_pk_bf16_f32 v42, v42, v43
	v_mul_f32_e32 v48, 0xbfb8aa3b, v46
	v_mul_f32_e32 v49, 0xbfb8aa3b, v47
	v_exp_f32_e32 v48, v48
	v_exp_f32_e32 v49, v49
	v_pk_mul_f32 v[36:37], v[36:37], v[50:51] op_sel_hi:[1,0]
	v_add_f32_e32 v48, 1.0, v48
	v_add_f32_e32 v49, 1.0, v49
	v_rcp_f32_e32 v48, v48
	v_rcp_f32_e32 v49, v49
	s_nop 0
	v_pk_mul_f32 v[46:47], v[46:47], v[48:49]
	s_nop 0
	v_pk_mul_f32 v[44:45], v[44:45], v[46:47]
	s_nop 0
	v_cvt_pk_bf16_f32 v43, v44, v45
	v_mad_i64_i32 v[44:45], s[22:23], v142, s11, v[122:123]
	v_lshl_add_u64 v[46:47], v[44:45], 0, v[124:125]
	global_store_dwordx2 v[46:47], v[42:43], off
	v_mul_f32_e32 v42, 0xbfb8aa3b, v38
	v_mul_f32_e32 v43, 0xbfb8aa3b, v39
	v_exp_f32_e32 v42, v42
	v_exp_f32_e32 v43, v43
; DI unsigned pk2(float lo, float hi) { fv2 v = {lo, hi}; return __builtin_bit_cast(unsigned, __builtin_convertvector(v, bfv2)); }
; DI float sigm(float x) { return rcpf(1.0f + ex2(-x * LOG2E)); }
;     DI void operator()(const AccT& acc, const Unit& u, int wr, int wc, int fr, int fq) const {
;     ...
;         for (int ai = 0; ai < 2; ++ai)
; #pragma unroll
;             for (int m = 0; m < 4; ++m) {
;                 const int row = u.pm * 256 + ai * 128 + wr * 64 + m * 16 + fr;
;                 const float rs = rsqrtf(sv_[ai][m] * (1.0f / 1024.0f) + EPS);
; #pragma unroll
;                 for (int bj = 0; bj < 2; ++bj) {
;                     const int col0 = u.pn * 256 + bj * 128 + wc * 32 + fq * 8;
;                     const f32x4 g = acc[ai][bj][m][0] * rs, uu = acc[ai][bj][m][1] * rs; f32x4 r;
; #pragma unroll
;                     for (int j = 0; j < 4; ++j) r[j] = g[j] * sigm(g[j]) * uu[j];
;                     u32x2 w; w.x = pk2(r[0], r[1]); w.y = pk2(r[2], r[3]); *(u32x2*)(ACT + (size_t)row * DFF + (col0 >> 1)) = w;
	v_add_f32_e32 v42, 1.0, v42
	v_add_f32_e32 v43, 1.0, v43
	v_rcp_f32_e32 v42, v42
	v_rcp_f32_e32 v43, v43
	s_nop 0
	v_pk_mul_f32 v[38:39], v[38:39], v[42:43]
	s_nop 0
	v_pk_mul_f32 v[34:35], v[34:35], v[38:39]
	v_pk_mul_f32 v[38:39], v[40:41], v[50:51] op_sel_hi:[1,0]
	v_cvt_pk_bf16_f32 v34, v34, v35
	v_mul_f32_e32 v40, 0xbfb8aa3b, v38
	v_mul_f32_e32 v41, 0xbfb8aa3b, v39
	v_exp_f32_e32 v40, v40
	v_exp_f32_e32 v41, v41
	v_add_f32_e32 v40, 1.0, v40
	v_add_f32_e32 v41, 1.0, v41
	v_rcp_f32_e32 v40, v40
	v_rcp_f32_e32 v41, v41
	s_nop 0
	v_pk_mul_f32 v[38:39], v[38:39], v[40:41]
	s_nop 0
	v_pk_mul_f32 v[36:37], v[36:37], v[38:39]
	s_nop 0
	v_cvt_pk_bf16_f32 v35, v36, v37
	v_lshl_add_u64 v[36:37], v[44:45], 0, v[114:115]
	global_store_dwordx2 v[36:37], v[34:35], off
	v_fmamk_f32 v34, v141, 0x3a800000, v225
	v_cmp_gt_f32_e32 vcc, s65, v34
	v_mul_f32_e32 v35, 0x4b800000, v34
	s_nop 0
	v_cndmask_b32_e32 v34, v34, v35, vcc
	v_rsq_f32_e32 v34, v34
	s_nop 0
	v_mul_f32_e32 v35, 0x45800000, v34
	v_cndmask_b32_e32 v34, v34, v35, vcc
	v_pk_mul_f32 v[30:31], v[30:31], v[34:35] op_sel_hi:[1,0]
	s_nop 0
	v_mul_f32_e32 v35, 0xbfb8aa3b, v30
	v_exp_f32_e32 v35, v35
	s_nop 0
	v_add_f32_e32 v35, 1.0, v35
	v_rcp_f32_e32 v36, v35
	v_mul_f32_e32 v35, 0xbfb8aa3b, v31
	v_exp_f32_e32 v35, v35
	s_nop 0
	v_add_f32_e32 v35, 1.0, v35
	v_rcp_f32_e32 v37, v35
	v_pk_mul_f32 v[26:27], v[26:27], v[34:35] op_sel_hi:[1,0]
	v_pk_mul_f32 v[28:29], v[28:29], v[34:35] op_sel_hi:[1,0]
	v_pk_mul_f32 v[22:23], v[22:23], v[34:35] op_sel_hi:[1,0]
	v_pk_mul_f32 v[30:31], v[30:31], v[36:37]
	v_pk_mul_f32 v[18:19], v[18:19], v[34:35] op_sel_hi:[1,0]
	v_pk_mul_f32 v[26:27], v[26:27], v[30:31]
	v_pk_mul_f32 v[30:31], v[32:33], v[34:35] op_sel_hi:[1,0]
	v_cvt_pk_bf16_f32 v26, v26, v27
	v_mul_f32_e32 v32, 0xbfb8aa3b, v30
	v_mul_f32_e32 v33, 0xbfb8aa3b, v31
	v_exp_f32_e32 v32, v32
	v_exp_f32_e32 v33, v33
	v_pk_mul_f32 v[20:21], v[20:21], v[34:35] op_sel_hi:[1,0]
	v_add_f32_e32 v32, 1.0, v32
	v_add_f32_e32 v33, 1.0, v33
	v_rcp_f32_e32 v32, v32
	v_rcp_f32_e32 v33, v33
	s_nop 0
	v_pk_mul_f32 v[30:31], v[30:31], v[32:33]
	s_nop 0
	v_pk_mul_f32 v[28:29], v[28:29], v[30:31]
	s_nop 0
	v_cvt_pk_bf16_f32 v27, v28, v29
	v_mad_i64_i32 v[28:29], s[22:23], v140, s11, v[122:123]
	v_lshl_add_u64 v[30:31], v[28:29], 0, v[124:125]
	global_store_dwordx2 v[30:31], v[26:27], off
	v_mul_f32_e32 v26, 0xbfb8aa3b, v22
	v_mul_f32_e32 v27, 0xbfb8aa3b, v23
	v_exp_f32_e32 v26, v26
	v_exp_f32_e32 v27, v27
	v_add_f32_e32 v26, 1.0, v26
	v_add_f32_e32 v27, 1.0, v27
	v_rcp_f32_e32 v26, v26
	v_rcp_f32_e32 v27, v27
	s_nop 0
	v_pk_mul_f32 v[22:23], v[22:23], v[26:27]
	s_nop 0
	v_pk_mul_f32 v[18:19], v[18:19], v[22:23]
	v_pk_mul_f32 v[22:23], v[24:25], v[34:35] op_sel_hi:[1,0]
	v_cvt_pk_bf16_f32 v18, v18, v19
	v_mul_f32_e32 v24, 0xbfb8aa3b, v22
	v_mul_f32_e32 v25, 0xbfb8aa3b, v23
	v_exp_f32_e32 v24, v24
	v_exp_f32_e32 v25, v25
	v_add_f32_e32 v24, 1.0, v24
	v_add_f32_e32 v25, 1.0, v25
	v_rcp_f32_e32 v24, v24
	v_rcp_f32_e32 v25, v25
	s_nop 0
	v_pk_mul_f32 v[22:23], v[22:23], v[24:25]
	s_nop 0
	v_pk_mul_f32 v[20:21], v[20:21], v[22:23]
	s_nop 0
	v_cvt_pk_bf16_f32 v19, v20, v21
	v_lshl_add_u64 v[20:21], v[28:29], 0, v[114:115]
	global_store_dwordx2 v[20:21], v[18:19], off
	v_fmamk_f32 v18, v139, 0x3a800000, v225
	v_cmp_gt_f32_e32 vcc, s65, v18
	v_mul_f32_e32 v19, 0x4b800000, v18
	s_nop 0
	v_cndmask_b32_e32 v18, v18, v19, vcc
	v_rsq_f32_e32 v18, v18
	s_nop 0
	v_mul_f32_e32 v19, 0x45800000, v18
	v_cndmask_b32_e32 v18, v18, v19, vcc
	v_pk_mul_f32 v[14:15], v[14:15], v[18:19] op_sel_hi:[1,0]
	s_and_b64 vcc, exec, s[12:13]
	v_mul_f32_e32 v19, 0xbfb8aa3b, v14
	v_exp_f32_e32 v19, v19
	s_nop 0
	v_add_f32_e32 v19, 1.0, v19
	v_rcp_f32_e32 v20, v19
	v_mul_f32_e32 v19, 0xbfb8aa3b, v15
	v_exp_f32_e32 v19, v19
	s_nop 0
	v_add_f32_e32 v19, 1.0, v19
	v_rcp_f32_e32 v21, v19
	v_pk_mul_f32 v[10:11], v[10:11], v[18:19] op_sel_hi:[1,0]
	v_pk_mul_f32 v[12:13], v[12:13], v[18:19] op_sel_hi:[1,0]
	v_pk_mul_f32 v[6:7], v[6:7], v[18:19] op_sel_hi:[1,0]
	v_pk_mul_f32 v[14:15], v[14:15], v[20:21]
	v_pk_mul_f32 v[2:3], v[2:3], v[18:19] op_sel_hi:[1,0]
	v_pk_mul_f32 v[10:11], v[10:11], v[14:15]
	v_pk_mul_f32 v[14:15], v[16:17], v[18:19] op_sel_hi:[1,0]
	v_cvt_pk_bf16_f32 v10, v10, v11
	v_mul_f32_e32 v16, 0xbfb8aa3b, v14
	v_mul_f32_e32 v17, 0xbfb8aa3b, v15
	v_exp_f32_e32 v16, v16
	v_exp_f32_e32 v17, v17
	v_pk_mul_f32 v[4:5], v[4:5], v[18:19] op_sel_hi:[1,0]
	v_add_f32_e32 v16, 1.0, v16
	v_add_f32_e32 v17, 1.0, v17
	v_rcp_f32_e32 v16, v16
	v_rcp_f32_e32 v17, v17
	s_nop 0
	v_pk_mul_f32 v[14:15], v[14:15], v[16:17]
	s_nop 0
	v_pk_mul_f32 v[12:13], v[12:13], v[14:15]
	s_nop 0
	v_cvt_pk_bf16_f32 v11, v12, v13
	v_mad_i64_i32 v[12:13], s[22:23], v135, s11, v[122:123]
	v_lshl_add_u64 v[14:15], v[12:13], 0, v[124:125]
	global_store_dwordx2 v[14:15], v[10:11], off
	v_mul_f32_e32 v10, 0xbfb8aa3b, v6
	v_mul_f32_e32 v11, 0xbfb8aa3b, v7
	v_exp_f32_e32 v10, v10
	v_exp_f32_e32 v11, v11
	s_mov_b64 s[22:23], s[16:17]
	v_add_f32_e32 v10, 1.0, v10
	v_add_f32_e32 v11, 1.0, v11
	v_rcp_f32_e32 v10, v10
	v_rcp_f32_e32 v11, v11
	s_nop 0
	v_pk_mul_f32 v[6:7], v[6:7], v[10:11]
	s_nop 0
	v_pk_mul_f32 v[2:3], v[2:3], v[6:7]
	v_pk_mul_f32 v[6:7], v[8:9], v[18:19] op_sel_hi:[1,0]
	v_cvt_pk_bf16_f32 v2, v2, v3
	v_mul_f32_e32 v8, 0xbfb8aa3b, v6
	v_mul_f32_e32 v9, 0xbfb8aa3b, v7
	v_exp_f32_e32 v8, v8
	v_exp_f32_e32 v9, v9
	v_add_f32_e32 v8, 1.0, v8
	v_add_f32_e32 v9, 1.0, v9
	v_rcp_f32_e32 v8, v8
	v_rcp_f32_e32 v9, v9
	s_nop 0
	v_pk_mul_f32 v[6:7], v[6:7], v[8:9]
	s_nop 0
	v_pk_mul_f32 v[4:5], v[4:5], v[6:7]
	s_nop 0
	v_cvt_pk_bf16_f32 v3, v4, v5
	v_lshl_add_u64 v[4:5], v[12:13], 0, v[114:115]
	global_store_dwordx2 v[4:5], v[2:3], off
	s_cbranch_vccz .LBB0_1783
	s_waitcnt vmcnt(0)
	s_cmpk_gt_u32 s20, 0xff
	s_cbranch_scc1 .LBB0_1790
	s_barrier
